# v65: all six GEMM K-loops issue their LDS-DMA loads at the start of each load interval, before the ds_reads (dataflow-checked reordering)
# speedup vs baseline: 1.0043x; 1.0043x over previous
; #define PG8_STAGE(bufoff, gbase) do { _Pragma("unroll") for (int _i = 0; _i < 2; ++_i) \
;         __builtin_amdgcn_global_load_lds((const unsigned*)((const char*)(gbase) + voff[_i]), (LAS unsigned*)(lds + (bufoff) + ldsw + _i * 8192), 16, 0, 0); } while (0)
; #define PG8_LDA(dst, b, h) do { _Pragma("unroll") for (int m = 0; m < 4; ++m) _Pragma("unroll") for (int k = 0; k < 2; ++k) dst[m][k] = *(const LAS bf16x8*)(lds + PG8_SA(b, h) + aoff + m * 2048 + k * 1024); } while (0)
; #define PG8_LDB(dst, b, h) do { _Pragma("unroll") for (int n = 0; n < 2; ++n) _Pragma("unroll") for (int k = 0; k < 2; ++k) dst[n][k] = *(const LAS bf16x8*)(lds + PG8_SB(b, h) + boff + n * 2048 + k * 1024); } while (0)
; #define PG8_MMA(ai, bj, At, Bt) do { __builtin_amdgcn_s_setprio(1); _Pragma("unroll") for (int m = 0; m < 4; ++m) _Pragma("unroll") for (int n = 0; n < 2; ++n) _Pragma("unroll") for (int k = 0; k < 2; ++k) \
;         acc[ai][bj][m][n] = __builtin_amdgcn_mfma_f32_16x16x32_bf16(Bt[n][k], At[m][k], acc[ai][bj][m][n], 0, 0, 0); __builtin_amdgcn_s_setprio(0); } while (0)
; #define PG8_WAIT_V(n) asm volatile("s_waitcnt vmcnt(" #n ")" ::: "memory")
; #define PG8_WAIT_L(n) asm volatile("s_waitcnt lgkmcnt(" #n ")" ::: "memory")
; #define PG8_BAR __builtin_amdgcn_s_barrier()
; #define PG8_SCHED __builtin_amdgcn_sched_barrier(0)
; template <int EPI> ...
;     ...
;             PG8_LDB(B0, 0, 0); PG8_LDB(B1, 0, 1); PG8_SCHED; PG8_LDA(At, 0, 0); PG8_STAGE(PG8_SA(1, 1), a1 + hstep);
;             PG8_WAIT_V(8); PG8_WAIT_L(0); PG8_BAR; PG8_MMA(0, 0, At, B0); PG8_MMA(0, 1, At, B1); PG8_BAR; PG8_SCHED;
;             PG8_LDA(At, 0, 1); PG8_STAGE(PG8_SB(0, 0), b2); PG8_STAGE(PG8_SB(0, 1), b2 + hstep); PG8_STAGE(PG8_SA(0, 0), a2);
;             PG8_WAIT_V(8); PG8_WAIT_L(0); PG8_BAR; PG8_MMA(1, 0, At, B0); PG8_MMA(1, 1, At, B1); PG8_BAR; PG8_SCHED;
.LBB0_137:
	s_add_u32 s28, s26, 0xfffc0080
	s_addc_u32 s29, s27, -1
	s_cmp_eq_u32 s36, 12
	s_cselect_b32 s31, s5, s29
	s_cselect_b32 s30, s7, s28
	s_cselect_b32 s29, s19, s35
	s_cselect_b32 s28, s21, s34
	v_lshl_add_u64 v[176:177], s[26:27], 0, v[156:157]
	s_add_i32 m0, s42, 0xc000
	s_nop 0
	global_load_lds_dwordx4 v[176:177], off
	v_lshl_add_u64 v[176:177], s[26:27], 0, v[158:159]
	s_add_i32 m0, s42, 0xe000
	s_nop 0
	global_load_lds_dwordx4 v[176:177], off
	ds_read_b128 v[130:133], v178
	ds_read_b128 v[164:167], v178 offset:1024
	ds_read_b128 v[168:171], v178 offset:2048
	ds_read_b128 v[172:175], v178 offset:3072
	ds_read_b128 v[188:191], v179
	ds_read_b128 v[192:195], v179 offset:1024
	ds_read_b128 v[196:199], v179 offset:2048
	ds_read_b128 v[200:203], v179 offset:3072
	ds_read_b128 v[204:207], v180
	ds_read_b128 v[208:211], v180 offset:1024
	ds_read_b128 v[212:215], v180 offset:2048
	ds_read_b128 v[216:219], v180 offset:3072
	ds_read_b128 v[220:223], v180 offset:4096
	ds_read_b128 v[224:227], v180 offset:5120
	ds_read_b128 v[228:231], v180 offset:6144
	ds_read_b128 v[232:235], v180 offset:7168
	s_waitcnt vmcnt(8)
	s_waitcnt lgkmcnt(0)
	s_barrier
	s_setprio 1
	s_waitcnt lgkmcnt(0)
	v_mfma_f32_16x16x32_bf16 v[126:129], v[130:133], v[204:207], v[126:129]
	v_mfma_f32_16x16x32_bf16 v[122:125], v[168:171], v[204:207], v[122:125]
	v_mfma_f32_16x16x32_bf16 v[118:121], v[130:133], v[212:215], v[118:121]
	v_mfma_f32_16x16x32_bf16 v[114:117], v[168:171], v[212:215], v[114:117]
	v_mfma_f32_16x16x32_bf16 v[110:113], v[130:133], v[220:223], v[110:113]
	v_mfma_f32_16x16x32_bf16 v[106:109], v[168:171], v[220:223], v[106:109]
	v_mfma_f32_16x16x32_bf16 v[102:105], v[130:133], v[228:231], v[102:105]
	v_mfma_f32_16x16x32_bf16 v[98:101], v[168:171], v[228:231], v[98:101]
	v_mfma_f32_16x16x32_bf16 v[126:129], v[164:167], v[208:211], v[126:129]
	v_mfma_f32_16x16x32_bf16 v[122:125], v[172:175], v[208:211], v[122:125]
	v_mfma_f32_16x16x32_bf16 v[118:121], v[164:167], v[216:219], v[118:121]
	v_mfma_f32_16x16x32_bf16 v[114:117], v[172:175], v[216:219], v[114:117]
	v_mfma_f32_16x16x32_bf16 v[110:113], v[164:167], v[224:227], v[110:113]
	v_mfma_f32_16x16x32_bf16 v[106:109], v[172:175], v[224:227], v[106:109]
	v_mfma_f32_16x16x32_bf16 v[102:105], v[164:167], v[232:235], v[102:105]
	v_mfma_f32_16x16x32_bf16 v[98:101], v[172:175], v[232:235], v[98:101]
	s_setprio 0
	s_setprio 1
	v_mfma_f32_16x16x32_bf16 v[62:65], v[188:191], v[204:207], v[62:65]
	v_mfma_f32_16x16x32_bf16 v[58:61], v[196:199], v[204:207], v[58:61]
	v_mfma_f32_16x16x32_bf16 v[54:57], v[188:191], v[212:215], v[54:57]
	v_mfma_f32_16x16x32_bf16 v[50:53], v[196:199], v[212:215], v[50:53]
	v_mfma_f32_16x16x32_bf16 v[46:49], v[188:191], v[220:223], v[46:49]
	v_mfma_f32_16x16x32_bf16 v[42:45], v[196:199], v[220:223], v[42:45]
	v_mfma_f32_16x16x32_bf16 v[38:41], v[188:191], v[228:231], v[38:41]
	v_mfma_f32_16x16x32_bf16 v[34:37], v[196:199], v[228:231], v[34:37]
	v_mfma_f32_16x16x32_bf16 v[62:65], v[192:195], v[208:211], v[62:65]
	v_mfma_f32_16x16x32_bf16 v[58:61], v[200:203], v[208:211], v[58:61]
	v_mfma_f32_16x16x32_bf16 v[54:57], v[192:195], v[216:219], v[54:57]
	v_mfma_f32_16x16x32_bf16 v[50:53], v[200:203], v[216:219], v[50:53]
	v_mfma_f32_16x16x32_bf16 v[46:49], v[192:195], v[224:227], v[46:49]
	v_mfma_f32_16x16x32_bf16 v[42:45], v[200:203], v[224:227], v[42:45]
	v_mfma_f32_16x16x32_bf16 v[38:41], v[192:195], v[232:235], v[38:41]
	v_mfma_f32_16x16x32_bf16 v[34:37], v[200:203], v[232:235], v[34:37]
	s_setprio 0
	s_barrier
	s_add_i32 s37, s55, s41
	v_lshl_add_u64 v[176:177], s[28:29], 0, v[136:137]
	s_mov_b32 m0, s37
	s_nop 0
	global_load_lds_dwordx4 v[176:177], off
	s_add_i32 m0, s37, 0x2000
	s_add_u32 s38, s28, 0x40000
	v_lshl_add_u64 v[236:237], s[28:29], 0, v[138:139]
	s_addc_u32 s39, s29, 0
	s_add_i32 s37, s56, s41
	global_load_lds_dwordx4 v[236:237], off
	v_lshl_add_u64 v[238:239], s[38:39], 0, v[136:137]
	s_mov_b32 m0, s37
	v_lshl_add_u64 v[240:241], s[30:31], 0, v[138:139]
	global_load_lds_dwordx4 v[238:239], off
	v_lshl_add_u64 v[238:239], s[38:39], 0, v[138:139]
	s_add_i32 m0, s37, 0x2000
	s_nop 0
	global_load_lds_dwordx4 v[238:239], off
	v_lshl_add_u64 v[238:239], s[30:31], 0, v[136:137]
	s_mov_b32 m0, s42
	s_nop 0
	global_load_lds_dwordx4 v[238:239], off
	s_mov_b32 m0, s43
	s_nop 0
	global_load_lds_dwordx4 v[240:241], off
	ds_read_b128 v[204:207], v180 offset:16384
	ds_read_b128 v[208:211], v180 offset:17408
	ds_read_b128 v[212:215], v180 offset:18432
	ds_read_b128 v[216:219], v180 offset:19456
	ds_read_b128 v[220:223], v180 offset:20480
	ds_read_b128 v[224:227], v180 offset:21504
	ds_read_b128 v[228:231], v180 offset:22528
	ds_read_b128 v[232:235], v180 offset:23552
	s_waitcnt vmcnt(8)
	s_waitcnt lgkmcnt(0)
	s_barrier
; #define PG8_STAGE(bufoff, gbase) do { _Pragma("unroll") for (int _i = 0; _i < 2; ++_i) \
;         __builtin_amdgcn_global_load_lds((const unsigned*)((const char*)(gbase) + voff[_i]), (LAS unsigned*)(lds + (bufoff) + ldsw + _i * 8192), 16, 0, 0); } while (0)
; #define PG8_LDA(dst, b, h) do { _Pragma("unroll") for (int m = 0; m < 4; ++m) _Pragma("unroll") for (int k = 0; k < 2; ++k) dst[m][k] = *(const LAS bf16x8*)(lds + PG8_SA(b, h) + aoff + m * 2048 + k * 1024); } while (0)
; #define PG8_LDB(dst, b, h) do { _Pragma("unroll") for (int n = 0; n < 2; ++n) _Pragma("unroll") for (int k = 0; k < 2; ++k) dst[n][k] = *(const LAS bf16x8*)(lds + PG8_SB(b, h) + boff + n * 2048 + k * 1024); } while (0)
; #define PG8_MMA(ai, bj, At, Bt) do { __builtin_amdgcn_s_setprio(1); _Pragma("unroll") for (int m = 0; m < 4; ++m) _Pragma("unroll") for (int n = 0; n < 2; ++n) _Pragma("unroll") for (int k = 0; k < 2; ++k) \
;         acc[ai][bj][m][n] = __builtin_amdgcn_mfma_f32_16x16x32_bf16(Bt[n][k], At[m][k], acc[ai][bj][m][n], 0, 0, 0); __builtin_amdgcn_s_setprio(0); } while (0)
; #define PG8_WAIT_V(n) asm volatile("s_waitcnt vmcnt(" #n ")" ::: "memory")
; #define PG8_WAIT_L(n) asm volatile("s_waitcnt lgkmcnt(" #n ")" ::: "memory")
; #define PG8_BAR __builtin_amdgcn_s_barrier()
; #define PG8_SCHED __builtin_amdgcn_sched_barrier(0)
; template <int EPI> ...
;     ...
;             PG8_WAIT_V(8); PG8_WAIT_L(0); PG8_BAR; PG8_MMA(1, 0, At, B0); PG8_MMA(1, 1, At, B1); PG8_BAR; PG8_SCHED;
;             PG8_LDB(B0, 1, 0); PG8_LDB(B1, 1, 1); PG8_SCHED; PG8_LDA(At, 1, 0); PG8_STAGE(PG8_SA(0, 1), a2 + hstep);
;             PG8_WAIT_V(8); PG8_WAIT_L(0); PG8_BAR; PG8_MMA(0, 0, At, B0); PG8_MMA(0, 1, At, B1); PG8_BAR; PG8_SCHED;
	s_setprio 1
	s_waitcnt lgkmcnt(0)
	v_mfma_f32_16x16x32_bf16 v[94:97], v[130:133], v[204:207], v[94:97]
	v_mfma_f32_16x16x32_bf16 v[90:93], v[168:171], v[204:207], v[90:93]
	v_mfma_f32_16x16x32_bf16 v[86:89], v[130:133], v[212:215], v[86:89]
	v_mfma_f32_16x16x32_bf16 v[82:85], v[168:171], v[212:215], v[82:85]
	v_mfma_f32_16x16x32_bf16 v[78:81], v[130:133], v[220:223], v[78:81]
	v_mfma_f32_16x16x32_bf16 v[74:77], v[168:171], v[220:223], v[74:77]
	v_mfma_f32_16x16x32_bf16 v[70:73], v[130:133], v[228:231], v[70:73]
	v_mfma_f32_16x16x32_bf16 v[66:69], v[168:171], v[228:231], v[66:69]
	v_mfma_f32_16x16x32_bf16 v[94:97], v[164:167], v[208:211], v[94:97]
	v_mfma_f32_16x16x32_bf16 v[90:93], v[172:175], v[208:211], v[90:93]
	v_mfma_f32_16x16x32_bf16 v[86:89], v[164:167], v[216:219], v[86:89]
	v_mfma_f32_16x16x32_bf16 v[82:85], v[172:175], v[216:219], v[82:85]
	v_mfma_f32_16x16x32_bf16 v[78:81], v[164:167], v[224:227], v[78:81]
	v_mfma_f32_16x16x32_bf16 v[74:77], v[172:175], v[224:227], v[74:77]
	v_mfma_f32_16x16x32_bf16 v[70:73], v[164:167], v[232:235], v[70:73]
	v_mfma_f32_16x16x32_bf16 v[66:69], v[172:175], v[232:235], v[66:69]
	s_setprio 0
	s_setprio 1
	v_mfma_f32_16x16x32_bf16 v[30:33], v[188:191], v[204:207], v[30:33]
	v_mfma_f32_16x16x32_bf16 v[26:29], v[196:199], v[204:207], v[26:29]
	v_mfma_f32_16x16x32_bf16 v[22:25], v[188:191], v[212:215], v[22:25]
	v_mfma_f32_16x16x32_bf16 v[18:21], v[196:199], v[212:215], v[18:21]
	v_mfma_f32_16x16x32_bf16 v[14:17], v[188:191], v[220:223], v[14:17]
	v_mfma_f32_16x16x32_bf16 v[10:13], v[196:199], v[220:223], v[10:13]
	v_mfma_f32_16x16x32_bf16 v[6:9], v[188:191], v[228:231], v[6:9]
	v_mfma_f32_16x16x32_bf16 v[2:5], v[196:199], v[228:231], v[2:5]
	v_mfma_f32_16x16x32_bf16 v[30:33], v[192:195], v[208:211], v[30:33]
	v_mfma_f32_16x16x32_bf16 v[26:29], v[200:203], v[208:211], v[26:29]
	v_mfma_f32_16x16x32_bf16 v[22:25], v[192:195], v[216:219], v[22:25]
	v_mfma_f32_16x16x32_bf16 v[18:21], v[200:203], v[216:219], v[18:21]
	v_mfma_f32_16x16x32_bf16 v[14:17], v[192:195], v[224:227], v[14:17]
	v_mfma_f32_16x16x32_bf16 v[10:13], v[200:203], v[224:227], v[10:13]
	v_mfma_f32_16x16x32_bf16 v[6:9], v[192:195], v[232:235], v[6:9]
	v_mfma_f32_16x16x32_bf16 v[2:5], v[200:203], v[232:235], v[2:5]
	s_setprio 0
	s_barrier
	s_add_i32 s37, 0, 0x18000
	s_add_i32 s38, 0, 0x1c000
	s_add_u32 s30, s30, 0x40000
	s_addc_u32 s31, s31, 0
	s_mov_b32 m0, s44
	v_lshl_add_u64 v[242:243], s[30:31], 0, v[136:137]
	global_load_lds_dwordx4 v[242:243], off
	v_lshl_add_u64 v[242:243], s[30:31], 0, v[138:139]
	s_mov_b32 m0, s45
	s_nop 0
	global_load_lds_dwordx4 v[242:243], off
	v_add_u32_e32 v140, s37, v147
	ds_read_b128 v[130:133], v140
	ds_read_b128 v[164:167], v140 offset:1024
	ds_read_b128 v[168:171], v140 offset:2048
	ds_read_b128 v[172:175], v140 offset:3072
	v_add_u32_e32 v140, s38, v147
	ds_read_b128 v[188:191], v140
	ds_read_b128 v[192:195], v140 offset:1024
	ds_read_b128 v[196:199], v140 offset:2048
	ds_read_b128 v[200:203], v140 offset:3072
	ds_read_b128 v[204:207], v180 offset:32768
	ds_read_b128 v[208:211], v180 offset:33792
	ds_read_b128 v[212:215], v180 offset:34816
	ds_read_b128 v[216:219], v180 offset:35840
	ds_read_b128 v[220:223], v180 offset:36864
	ds_read_b128 v[224:227], v180 offset:37888
	ds_read_b128 v[228:231], v180 offset:38912
	ds_read_b128 v[232:235], v180 offset:39936
	s_waitcnt vmcnt(8)
	s_waitcnt lgkmcnt(0)
	s_barrier
	s_setprio 1
	s_waitcnt lgkmcnt(0)
	v_mfma_f32_16x16x32_bf16 v[126:129], v[130:133], v[204:207], v[126:129]
	v_mfma_f32_16x16x32_bf16 v[122:125], v[168:171], v[204:207], v[122:125]
	v_mfma_f32_16x16x32_bf16 v[118:121], v[130:133], v[212:215], v[118:121]
	v_mfma_f32_16x16x32_bf16 v[114:117], v[168:171], v[212:215], v[114:117]
	v_mfma_f32_16x16x32_bf16 v[110:113], v[130:133], v[220:223], v[110:113]
	v_mfma_f32_16x16x32_bf16 v[106:109], v[168:171], v[220:223], v[106:109]
	v_mfma_f32_16x16x32_bf16 v[102:105], v[130:133], v[228:231], v[102:105]
	v_mfma_f32_16x16x32_bf16 v[98:101], v[168:171], v[228:231], v[98:101]
	v_mfma_f32_16x16x32_bf16 v[126:129], v[164:167], v[208:211], v[126:129]
	v_mfma_f32_16x16x32_bf16 v[122:125], v[172:175], v[208:211], v[122:125]
	v_mfma_f32_16x16x32_bf16 v[118:121], v[164:167], v[216:219], v[118:121]
	v_mfma_f32_16x16x32_bf16 v[114:117], v[172:175], v[216:219], v[114:117]
	v_mfma_f32_16x16x32_bf16 v[110:113], v[164:167], v[224:227], v[110:113]
	v_mfma_f32_16x16x32_bf16 v[106:109], v[172:175], v[224:227], v[106:109]
	v_mfma_f32_16x16x32_bf16 v[102:105], v[164:167], v[232:235], v[102:105]
	v_mfma_f32_16x16x32_bf16 v[98:101], v[172:175], v[232:235], v[98:101]
	s_setprio 0
	s_setprio 1
	v_mfma_f32_16x16x32_bf16 v[62:65], v[188:191], v[204:207], v[62:65]
	v_mfma_f32_16x16x32_bf16 v[58:61], v[196:199], v[204:207], v[58:61]
	v_mfma_f32_16x16x32_bf16 v[54:57], v[188:191], v[212:215], v[54:57]
	v_mfma_f32_16x16x32_bf16 v[50:53], v[196:199], v[212:215], v[50:53]
	v_mfma_f32_16x16x32_bf16 v[46:49], v[188:191], v[220:223], v[46:49]
	v_mfma_f32_16x16x32_bf16 v[42:45], v[196:199], v[220:223], v[42:45]
	v_mfma_f32_16x16x32_bf16 v[38:41], v[188:191], v[228:231], v[38:41]
	v_mfma_f32_16x16x32_bf16 v[34:37], v[196:199], v[228:231], v[34:37]
	v_mfma_f32_16x16x32_bf16 v[62:65], v[192:195], v[208:211], v[62:65]
	v_mfma_f32_16x16x32_bf16 v[58:61], v[200:203], v[208:211], v[58:61]
	v_mfma_f32_16x16x32_bf16 v[54:57], v[192:195], v[216:219], v[54:57]
	v_mfma_f32_16x16x32_bf16 v[50:53], v[200:203], v[216:219], v[50:53]
	v_mfma_f32_16x16x32_bf16 v[46:49], v[192:195], v[224:227], v[46:49]
	v_mfma_f32_16x16x32_bf16 v[42:45], v[200:203], v[224:227], v[42:45]
	v_mfma_f32_16x16x32_bf16 v[38:41], v[192:195], v[232:235], v[38:41]
	v_mfma_f32_16x16x32_bf16 v[34:37], v[200:203], v[232:235], v[34:37]
	s_setprio 0
	s_barrier
; #define PG8_STAGE(bufoff, gbase) do { _Pragma("unroll") for (int _i = 0; _i < 2; ++_i) \
;         __builtin_amdgcn_global_load_lds((const unsigned*)((const char*)(gbase) + voff[_i]), (LAS unsigned*)(lds + (bufoff) + ldsw + _i * 8192), 16, 0, 0); } while (0)
; #define PG8_LDA(dst, b, h) do { _Pragma("unroll") for (int m = 0; m < 4; ++m) _Pragma("unroll") for (int k = 0; k < 2; ++k) dst[m][k] = *(const LAS bf16x8*)(lds + PG8_SA(b, h) + aoff + m * 2048 + k * 1024); } while (0)
; #define PG8_MMA(ai, bj, At, Bt) do { __builtin_amdgcn_s_setprio(1); _Pragma("unroll") for (int m = 0; m < 4; ++m) _Pragma("unroll") for (int n = 0; n < 2; ++n) _Pragma("unroll") for (int k = 0; k < 2; ++k) \
;         acc[ai][bj][m][n] = __builtin_amdgcn_mfma_f32_16x16x32_bf16(Bt[n][k], At[m][k], acc[ai][bj][m][n], 0, 0, 0); __builtin_amdgcn_s_setprio(0); } while (0)
; #define PG8_WAIT_V(n) asm volatile("s_waitcnt vmcnt(" #n ")" ::: "memory")
; #define PG8_WAIT_L(n) asm volatile("s_waitcnt lgkmcnt(" #n ")" ::: "memory")
; #define PG8_BAR __builtin_amdgcn_s_barrier()
; #define PG8_SCHED __builtin_amdgcn_sched_barrier(0)
; template <int EPI> ...
;     ...
;             PG8_LDA(At, 1, 1); PG8_STAGE(PG8_SB(1, 0), b3); PG8_STAGE(PG8_SB(1, 1), b3 + hstep); PG8_STAGE(PG8_SA(1, 0), a3);
;             PG8_WAIT_V(8); PG8_WAIT_L(0); PG8_BAR; PG8_MMA(1, 0, At, B0); PG8_MMA(1, 1, At, B1); PG8_BAR; PG8_SCHED;
;         }
	s_add_i32 s30, s37, s41
	v_lshl_add_u64 v[176:177], v[176:177], 0, s[10:11]
	s_mov_b32 m0, s30
	s_nop 0
	global_load_lds_dwordx4 v[176:177], off
	s_add_i32 m0, s30, 0x2000
	s_add_u32 s28, s28, 0x40080
	v_lshl_add_u64 v[176:177], v[236:237], 0, s[10:11]
	s_addc_u32 s29, s29, 0
	s_add_i32 s30, s38, s41
	global_load_lds_dwordx4 v[176:177], off
	v_lshl_add_u64 v[176:177], s[28:29], 0, v[136:137]
	s_mov_b32 m0, s30
	s_nop 0
	global_load_lds_dwordx4 v[176:177], off
	v_lshl_add_u64 v[176:177], s[28:29], 0, v[138:139]
	s_add_i32 m0, s30, 0x2000
	s_nop 0
	global_load_lds_dwordx4 v[176:177], off
	v_lshl_add_u64 v[176:177], v[238:239], 0, s[10:11]
	s_mov_b32 m0, s48
	s_nop 0
	global_load_lds_dwordx4 v[176:177], off
	v_lshl_add_u64 v[176:177], v[240:241], 0, s[10:11]
	s_mov_b32 m0, s49
	s_nop 0
	global_load_lds_dwordx4 v[176:177], off
	ds_read_b128 v[204:207], v180 offset:49152
	ds_read_b128 v[208:211], v180 offset:50176
	ds_read_b128 v[212:215], v180 offset:51200
	ds_read_b128 v[216:219], v180 offset:52224
	ds_read_b128 v[220:223], v180 offset:53248
	ds_read_b128 v[224:227], v180 offset:54272
	ds_read_b128 v[228:231], v180 offset:55296
	ds_read_b128 v[232:235], v180 offset:56320
	s_waitcnt vmcnt(8)
	s_waitcnt lgkmcnt(0)
	s_barrier
	s_setprio 1
	s_waitcnt lgkmcnt(0)
	v_mfma_f32_16x16x32_bf16 v[94:97], v[130:133], v[204:207], v[94:97]
	v_mfma_f32_16x16x32_bf16 v[90:93], v[168:171], v[204:207], v[90:93]
	v_mfma_f32_16x16x32_bf16 v[86:89], v[130:133], v[212:215], v[86:89]
	v_mfma_f32_16x16x32_bf16 v[82:85], v[168:171], v[212:215], v[82:85]
	v_mfma_f32_16x16x32_bf16 v[78:81], v[130:133], v[220:223], v[78:81]
	v_mfma_f32_16x16x32_bf16 v[74:77], v[168:171], v[220:223], v[74:77]
	v_mfma_f32_16x16x32_bf16 v[70:73], v[130:133], v[228:231], v[70:73]
	v_mfma_f32_16x16x32_bf16 v[66:69], v[168:171], v[228:231], v[66:69]
	v_mfma_f32_16x16x32_bf16 v[94:97], v[164:167], v[208:211], v[94:97]
	v_mfma_f32_16x16x32_bf16 v[90:93], v[172:175], v[208:211], v[90:93]
	v_mfma_f32_16x16x32_bf16 v[86:89], v[164:167], v[216:219], v[86:89]
	v_mfma_f32_16x16x32_bf16 v[82:85], v[172:175], v[216:219], v[82:85]
	v_mfma_f32_16x16x32_bf16 v[78:81], v[164:167], v[224:227], v[78:81]
	v_mfma_f32_16x16x32_bf16 v[74:77], v[172:175], v[224:227], v[74:77]
	v_mfma_f32_16x16x32_bf16 v[70:73], v[164:167], v[232:235], v[70:73]
	v_mfma_f32_16x16x32_bf16 v[66:69], v[172:175], v[232:235], v[66:69]
	s_setprio 0
	s_setprio 1
	v_mfma_f32_16x16x32_bf16 v[30:33], v[188:191], v[204:207], v[30:33]
	v_mfma_f32_16x16x32_bf16 v[26:29], v[196:199], v[204:207], v[26:29]
	v_mfma_f32_16x16x32_bf16 v[22:25], v[188:191], v[212:215], v[22:25]
	v_mfma_f32_16x16x32_bf16 v[18:21], v[196:199], v[212:215], v[18:21]
	v_mfma_f32_16x16x32_bf16 v[14:17], v[188:191], v[220:223], v[14:17]
	v_mfma_f32_16x16x32_bf16 v[10:13], v[196:199], v[220:223], v[10:13]
	v_mfma_f32_16x16x32_bf16 v[6:9], v[188:191], v[228:231], v[6:9]
	v_mfma_f32_16x16x32_bf16 v[2:5], v[196:199], v[228:231], v[2:5]
	v_mfma_f32_16x16x32_bf16 v[30:33], v[192:195], v[208:211], v[30:33]
	v_mfma_f32_16x16x32_bf16 v[26:29], v[200:203], v[208:211], v[26:29]
	v_mfma_f32_16x16x32_bf16 v[22:25], v[192:195], v[216:219], v[22:25]
	v_mfma_f32_16x16x32_bf16 v[18:21], v[200:203], v[216:219], v[18:21]
	v_mfma_f32_16x16x32_bf16 v[14:17], v[192:195], v[224:227], v[14:17]
	v_mfma_f32_16x16x32_bf16 v[10:13], v[200:203], v[224:227], v[10:13]
	v_mfma_f32_16x16x32_bf16 v[6:9], v[192:195], v[232:235], v[6:9]
	v_mfma_f32_16x16x32_bf16 v[2:5], v[200:203], v[232:235], v[2:5]
	s_setprio 0
	s_barrier
	s_add_i32 s36, s36, 2
	s_add_u32 s26, s26, 0x100
	s_addc_u32 s27, s27, 0
	s_add_u32 s34, s34, 0x100
	s_addc_u32 s35, s35, 0
	s_cmp_gt_u32 s36, 13
	s_cbranch_scc0 .LBB0_137
	s_and_b64 vcc, exec, s[12:13]
	s_cbranch_vccz .LBB0_140
	s_barrier

; #define PG8_STAGE(bufoff, gbase) do { _Pragma("unroll") for (int _i = 0; _i < 2; ++_i) \
;         __builtin_amdgcn_global_load_lds((const unsigned*)((const char*)(gbase) + voff[_i]), (LAS unsigned*)(lds + (bufoff) + ldsw + _i * 8192), 16, 0, 0); } while (0)
; #define PG8_LDA(dst, b, h) do { _Pragma("unroll") for (int m = 0; m < 4; ++m) _Pragma("unroll") for (int k = 0; k < 2; ++k) dst[m][k] = *(const LAS bf16x8*)(lds + PG8_SA(b, h) + aoff + m * 2048 + k * 1024); } while (0)
; #define PG8_LDB(dst, b, h) do { _Pragma("unroll") for (int n = 0; n < 2; ++n) _Pragma("unroll") for (int k = 0; k < 2; ++k) dst[n][k] = *(const LAS bf16x8*)(lds + PG8_SB(b, h) + boff + n * 2048 + k * 1024); } while (0)
; #define PG8_MMA(ai, bj, At, Bt) do { __builtin_amdgcn_s_setprio(1); _Pragma("unroll") for (int m = 0; m < 4; ++m) _Pragma("unroll") for (int n = 0; n < 2; ++n) _Pragma("unroll") for (int k = 0; k < 2; ++k) \
;         acc[ai][bj][m][n] = __builtin_amdgcn_mfma_f32_16x16x32_bf16(Bt[n][k], At[m][k], acc[ai][bj][m][n], 0, 0, 0); __builtin_amdgcn_s_setprio(0); } while (0)
; #define PG8_WAIT_V(n) asm volatile("s_waitcnt vmcnt(" #n ")" ::: "memory")
; #define PG8_WAIT_L(n) asm volatile("s_waitcnt lgkmcnt(" #n ")" ::: "memory")
; #define PG8_BAR __builtin_amdgcn_s_barrier()
; #define PG8_SCHED __builtin_amdgcn_sched_barrier(0)
; template <int EPI> ...
;     ...
;             PG8_LDB(B0, 0, 0); PG8_LDB(B1, 0, 1); PG8_SCHED; PG8_LDA(At, 0, 0); PG8_STAGE(PG8_SA(1, 1), a1 + hstep);
;             PG8_WAIT_V(8); PG8_WAIT_L(0); PG8_BAR; PG8_MMA(0, 0, At, B0); PG8_MMA(0, 1, At, B1); PG8_BAR; PG8_SCHED;
;             PG8_LDA(At, 0, 1); PG8_STAGE(PG8_SB(0, 0), b2); PG8_STAGE(PG8_SB(0, 1), b2 + hstep); PG8_STAGE(PG8_SA(0, 0), a2);
;             PG8_WAIT_V(8); PG8_WAIT_L(0); PG8_BAR; PG8_MMA(1, 0, At, B0); PG8_MMA(1, 1, At, B1); PG8_BAR; PG8_SCHED;
.LBB0_656:
	s_add_i32 s63, s62, 2
	s_add_u32 s28, s26, 0xfffe0080
	s_addc_u32 s29, s27, -1
	s_cmp_eq_u32 s59, s62
	s_cselect_b32 s31, s5, s29
	s_cselect_b32 s30, s19, s28
	s_cselect_b32 s29, s17, s61
	s_cselect_b32 s28, s58, s60
	v_lshl_add_u64 v[224:225], s[26:27], 0, v[136:137]
	s_add_i32 m0, s7, 0xc000
	s_nop 0
	global_load_lds_dwordx4 v[224:225], off
	v_lshl_add_u64 v[224:225], s[26:27], 0, v[138:139]
	s_add_i32 m0, s7, 0xe000
	s_nop 0
	global_load_lds_dwordx4 v[224:225], off
	ds_read_b128 v[142:145], v158
	ds_read_b128 v[146:149], v158 offset:1024
	ds_read_b128 v[162:165], v158 offset:2048
	ds_read_b128 v[166:169], v158 offset:3072
	ds_read_b128 v[170:173], v159
	ds_read_b128 v[174:177], v159 offset:1024
	ds_read_b128 v[178:181], v159 offset:2048
	ds_read_b128 v[188:191], v159 offset:3072
	ds_read_b128 v[192:195], v160
	ds_read_b128 v[196:199], v160 offset:1024
	ds_read_b128 v[200:203], v160 offset:2048
	ds_read_b128 v[204:207], v160 offset:3072
	ds_read_b128 v[208:211], v160 offset:4096
	ds_read_b128 v[212:215], v160 offset:5120
	ds_read_b128 v[216:219], v160 offset:6144
	ds_read_b128 v[220:223], v160 offset:7168
	s_waitcnt vmcnt(8)
	s_waitcnt lgkmcnt(0)
	s_barrier
	s_setprio 1
	s_waitcnt lgkmcnt(0)
	v_mfma_f32_16x16x32_bf16 v[126:129], v[142:145], v[192:195], v[126:129]
	v_mfma_f32_16x16x32_bf16 v[122:125], v[162:165], v[192:195], v[122:125]
	v_mfma_f32_16x16x32_bf16 v[118:121], v[142:145], v[200:203], v[118:121]
	v_mfma_f32_16x16x32_bf16 v[114:117], v[162:165], v[200:203], v[114:117]
	v_mfma_f32_16x16x32_bf16 v[106:109], v[142:145], v[208:211], v[106:109]
	v_mfma_f32_16x16x32_bf16 v[98:101], v[162:165], v[208:211], v[98:101]
	v_mfma_f32_16x16x32_bf16 v[90:93], v[142:145], v[216:219], v[90:93]
	v_mfma_f32_16x16x32_bf16 v[82:85], v[162:165], v[216:219], v[82:85]
	v_mfma_f32_16x16x32_bf16 v[126:129], v[146:149], v[196:199], v[126:129]
	v_mfma_f32_16x16x32_bf16 v[122:125], v[166:169], v[196:199], v[122:125]
	v_mfma_f32_16x16x32_bf16 v[118:121], v[146:149], v[204:207], v[118:121]
	v_mfma_f32_16x16x32_bf16 v[114:117], v[166:169], v[204:207], v[114:117]
	v_mfma_f32_16x16x32_bf16 v[106:109], v[146:149], v[212:215], v[106:109]
	v_mfma_f32_16x16x32_bf16 v[98:101], v[166:169], v[212:215], v[98:101]
	v_mfma_f32_16x16x32_bf16 v[90:93], v[146:149], v[220:223], v[90:93]
	v_mfma_f32_16x16x32_bf16 v[82:85], v[166:169], v[220:223], v[82:85]
	s_setprio 0
	s_setprio 1
	v_mfma_f32_16x16x32_bf16 v[110:113], v[170:173], v[192:195], v[110:113]
	v_mfma_f32_16x16x32_bf16 v[102:105], v[178:181], v[192:195], v[102:105]
	v_mfma_f32_16x16x32_bf16 v[94:97], v[170:173], v[200:203], v[94:97]
	v_mfma_f32_16x16x32_bf16 v[86:89], v[178:181], v[200:203], v[86:89]
	v_mfma_f32_16x16x32_bf16 v[78:81], v[170:173], v[208:211], v[78:81]
	v_mfma_f32_16x16x32_bf16 v[74:77], v[178:181], v[208:211], v[74:77]
	v_mfma_f32_16x16x32_bf16 v[70:73], v[170:173], v[216:219], v[70:73]
	v_mfma_f32_16x16x32_bf16 v[66:69], v[178:181], v[216:219], v[66:69]
	v_mfma_f32_16x16x32_bf16 v[110:113], v[174:177], v[196:199], v[110:113]
	v_mfma_f32_16x16x32_bf16 v[102:105], v[188:191], v[196:199], v[102:105]
	v_mfma_f32_16x16x32_bf16 v[94:97], v[174:177], v[204:207], v[94:97]
	v_mfma_f32_16x16x32_bf16 v[86:89], v[188:191], v[204:207], v[86:89]
	v_mfma_f32_16x16x32_bf16 v[78:81], v[174:177], v[212:215], v[78:81]
	v_mfma_f32_16x16x32_bf16 v[74:77], v[188:191], v[212:215], v[74:77]
	v_mfma_f32_16x16x32_bf16 v[70:73], v[174:177], v[220:223], v[70:73]
	v_mfma_f32_16x16x32_bf16 v[66:69], v[188:191], v[220:223], v[66:69]
	s_setprio 0
	s_barrier
	s_add_i32 s62, s48, s40
	v_lshl_add_u64 v[224:225], s[28:29], 0, v[130:131]
	s_mov_b32 m0, s62
	s_nop 0
	global_load_lds_dwordx4 v[224:225], off
	s_add_i32 m0, s62, 0x2000
	s_add_u32 s64, s28, 0x20000
	v_lshl_add_u64 v[226:227], s[28:29], 0, v[132:133]
	s_addc_u32 s65, s29, 0
	s_add_i32 s62, s49, s40
	global_load_lds_dwordx4 v[226:227], off
	v_lshl_add_u64 v[228:229], s[64:65], 0, v[130:131]
	s_mov_b32 m0, s62
	v_lshl_add_u64 v[230:231], s[30:31], 0, v[132:133]
	global_load_lds_dwordx4 v[228:229], off
	v_lshl_add_u64 v[228:229], s[64:65], 0, v[132:133]
	s_add_i32 m0, s62, 0x2000
	s_nop 0
	global_load_lds_dwordx4 v[228:229], off
	v_lshl_add_u64 v[228:229], s[30:31], 0, v[130:131]
	s_mov_b32 m0, s7
	s_nop 0
	global_load_lds_dwordx4 v[228:229], off
	s_mov_b32 m0, s42
	s_nop 0
	global_load_lds_dwordx4 v[230:231], off
	ds_read_b128 v[192:195], v160 offset:16384
	ds_read_b128 v[196:199], v160 offset:17408
	ds_read_b128 v[200:203], v160 offset:18432
	ds_read_b128 v[204:207], v160 offset:19456
	ds_read_b128 v[208:211], v160 offset:20480
	ds_read_b128 v[212:215], v160 offset:21504
	ds_read_b128 v[216:219], v160 offset:22528
	ds_read_b128 v[220:223], v160 offset:23552
	s_waitcnt vmcnt(8)
	s_waitcnt lgkmcnt(0)
	s_barrier
; #define PG8_STAGE(bufoff, gbase) do { _Pragma("unroll") for (int _i = 0; _i < 2; ++_i) \
;         __builtin_amdgcn_global_load_lds((const unsigned*)((const char*)(gbase) + voff[_i]), (LAS unsigned*)(lds + (bufoff) + ldsw + _i * 8192), 16, 0, 0); } while (0)
; #define PG8_LDA(dst, b, h) do { _Pragma("unroll") for (int m = 0; m < 4; ++m) _Pragma("unroll") for (int k = 0; k < 2; ++k) dst[m][k] = *(const LAS bf16x8*)(lds + PG8_SA(b, h) + aoff + m * 2048 + k * 1024); } while (0)
; #define PG8_LDB(dst, b, h) do { _Pragma("unroll") for (int n = 0; n < 2; ++n) _Pragma("unroll") for (int k = 0; k < 2; ++k) dst[n][k] = *(const LAS bf16x8*)(lds + PG8_SB(b, h) + boff + n * 2048 + k * 1024); } while (0)
; #define PG8_MMA(ai, bj, At, Bt) do { __builtin_amdgcn_s_setprio(1); _Pragma("unroll") for (int m = 0; m < 4; ++m) _Pragma("unroll") for (int n = 0; n < 2; ++n) _Pragma("unroll") for (int k = 0; k < 2; ++k) \
;         acc[ai][bj][m][n] = __builtin_amdgcn_mfma_f32_16x16x32_bf16(Bt[n][k], At[m][k], acc[ai][bj][m][n], 0, 0, 0); __builtin_amdgcn_s_setprio(0); } while (0)
; #define PG8_WAIT_V(n) asm volatile("s_waitcnt vmcnt(" #n ")" ::: "memory")
; #define PG8_WAIT_L(n) asm volatile("s_waitcnt lgkmcnt(" #n ")" ::: "memory")
; #define PG8_BAR __builtin_amdgcn_s_barrier()
; #define PG8_SCHED __builtin_amdgcn_sched_barrier(0)
; template <int EPI> ...
;     ...
;             PG8_WAIT_V(8); PG8_WAIT_L(0); PG8_BAR; PG8_MMA(1, 0, At, B0); PG8_MMA(1, 1, At, B1); PG8_BAR; PG8_SCHED;
;             PG8_LDB(B0, 1, 0); PG8_LDB(B1, 1, 1); PG8_SCHED; PG8_LDA(At, 1, 0); PG8_STAGE(PG8_SA(0, 1), a2 + hstep);
;             PG8_WAIT_V(8); PG8_WAIT_L(0); PG8_BAR; PG8_MMA(0, 0, At, B0); PG8_MMA(0, 1, At, B1); PG8_BAR; PG8_SCHED;
	s_setprio 1
	s_waitcnt lgkmcnt(0)
	v_mfma_f32_16x16x32_bf16 v[62:65], v[142:145], v[192:195], v[62:65]
	v_mfma_f32_16x16x32_bf16 v[58:61], v[162:165], v[192:195], v[58:61]
	v_mfma_f32_16x16x32_bf16 v[54:57], v[142:145], v[200:203], v[54:57]
	v_mfma_f32_16x16x32_bf16 v[50:53], v[162:165], v[200:203], v[50:53]
	v_mfma_f32_16x16x32_bf16 v[42:45], v[142:145], v[208:211], v[42:45]
	v_mfma_f32_16x16x32_bf16 v[34:37], v[162:165], v[208:211], v[34:37]
	v_mfma_f32_16x16x32_bf16 v[26:29], v[142:145], v[216:219], v[26:29]
	v_mfma_f32_16x16x32_bf16 v[18:21], v[162:165], v[216:219], v[18:21]
	v_mfma_f32_16x16x32_bf16 v[62:65], v[146:149], v[196:199], v[62:65]
	v_mfma_f32_16x16x32_bf16 v[58:61], v[166:169], v[196:199], v[58:61]
	v_mfma_f32_16x16x32_bf16 v[54:57], v[146:149], v[204:207], v[54:57]
	v_mfma_f32_16x16x32_bf16 v[50:53], v[166:169], v[204:207], v[50:53]
	v_mfma_f32_16x16x32_bf16 v[42:45], v[146:149], v[212:215], v[42:45]
	v_mfma_f32_16x16x32_bf16 v[34:37], v[166:169], v[212:215], v[34:37]
	v_mfma_f32_16x16x32_bf16 v[26:29], v[146:149], v[220:223], v[26:29]
	v_mfma_f32_16x16x32_bf16 v[18:21], v[166:169], v[220:223], v[18:21]
	s_setprio 0
	s_setprio 1
	v_mfma_f32_16x16x32_bf16 v[46:49], v[170:173], v[192:195], v[46:49]
	v_mfma_f32_16x16x32_bf16 v[38:41], v[178:181], v[192:195], v[38:41]
	v_mfma_f32_16x16x32_bf16 v[30:33], v[170:173], v[200:203], v[30:33]
	v_mfma_f32_16x16x32_bf16 v[22:25], v[178:181], v[200:203], v[22:25]
	v_mfma_f32_16x16x32_bf16 v[14:17], v[170:173], v[208:211], v[14:17]
	v_mfma_f32_16x16x32_bf16 v[10:13], v[178:181], v[208:211], v[10:13]
	v_mfma_f32_16x16x32_bf16 v[6:9], v[170:173], v[216:219], v[6:9]
	v_mfma_f32_16x16x32_bf16 v[2:5], v[178:181], v[216:219], v[2:5]
	v_mfma_f32_16x16x32_bf16 v[46:49], v[174:177], v[196:199], v[46:49]
	v_mfma_f32_16x16x32_bf16 v[38:41], v[188:191], v[196:199], v[38:41]
	v_mfma_f32_16x16x32_bf16 v[30:33], v[174:177], v[204:207], v[30:33]
	v_mfma_f32_16x16x32_bf16 v[22:25], v[188:191], v[204:207], v[22:25]
	v_mfma_f32_16x16x32_bf16 v[14:17], v[174:177], v[212:215], v[14:17]
	v_mfma_f32_16x16x32_bf16 v[10:13], v[188:191], v[212:215], v[10:13]
	v_mfma_f32_16x16x32_bf16 v[6:9], v[174:177], v[220:223], v[6:9]
	v_mfma_f32_16x16x32_bf16 v[2:5], v[188:191], v[220:223], v[2:5]
	s_setprio 0
	s_barrier
	s_add_i32 s62, 0, 0x18000
	s_add_i32 s64, 0, 0x1c000
	s_add_u32 s30, s30, 0x20000
	s_addc_u32 s31, s31, 0
	s_mov_b32 m0, s43
	v_lshl_add_u64 v[232:233], s[30:31], 0, v[130:131]
	global_load_lds_dwordx4 v[232:233], off
	v_lshl_add_u64 v[232:233], s[30:31], 0, v[132:133]
	s_mov_b32 m0, s44
	s_nop 0
	global_load_lds_dwordx4 v[232:233], off
	v_add_u32_e32 v134, s62, v152
	ds_read_b128 v[142:145], v134
	ds_read_b128 v[146:149], v134 offset:1024
	ds_read_b128 v[162:165], v134 offset:2048
	ds_read_b128 v[166:169], v134 offset:3072
	v_add_u32_e32 v134, s64, v152
	ds_read_b128 v[170:173], v134
	ds_read_b128 v[174:177], v134 offset:1024
	ds_read_b128 v[178:181], v134 offset:2048
	ds_read_b128 v[188:191], v134 offset:3072
	ds_read_b128 v[192:195], v160 offset:32768
	ds_read_b128 v[196:199], v160 offset:33792
	ds_read_b128 v[200:203], v160 offset:34816
	ds_read_b128 v[204:207], v160 offset:35840
	ds_read_b128 v[208:211], v160 offset:36864
	ds_read_b128 v[212:215], v160 offset:37888
	ds_read_b128 v[216:219], v160 offset:38912
	ds_read_b128 v[220:223], v160 offset:39936
	s_waitcnt vmcnt(8)
	s_waitcnt lgkmcnt(0)
	s_barrier
	s_setprio 1
	s_waitcnt lgkmcnt(0)
	v_mfma_f32_16x16x32_bf16 v[126:129], v[142:145], v[192:195], v[126:129]
	v_mfma_f32_16x16x32_bf16 v[122:125], v[162:165], v[192:195], v[122:125]
	v_mfma_f32_16x16x32_bf16 v[118:121], v[142:145], v[200:203], v[118:121]
	v_mfma_f32_16x16x32_bf16 v[114:117], v[162:165], v[200:203], v[114:117]
	v_mfma_f32_16x16x32_bf16 v[106:109], v[142:145], v[208:211], v[106:109]
	v_mfma_f32_16x16x32_bf16 v[98:101], v[162:165], v[208:211], v[98:101]
	v_mfma_f32_16x16x32_bf16 v[90:93], v[142:145], v[216:219], v[90:93]
	v_mfma_f32_16x16x32_bf16 v[82:85], v[162:165], v[216:219], v[82:85]
	v_mfma_f32_16x16x32_bf16 v[126:129], v[146:149], v[196:199], v[126:129]
	v_mfma_f32_16x16x32_bf16 v[122:125], v[166:169], v[196:199], v[122:125]
	v_mfma_f32_16x16x32_bf16 v[118:121], v[146:149], v[204:207], v[118:121]
	v_mfma_f32_16x16x32_bf16 v[114:117], v[166:169], v[204:207], v[114:117]
	v_mfma_f32_16x16x32_bf16 v[106:109], v[146:149], v[212:215], v[106:109]
	v_mfma_f32_16x16x32_bf16 v[98:101], v[166:169], v[212:215], v[98:101]
	v_mfma_f32_16x16x32_bf16 v[90:93], v[146:149], v[220:223], v[90:93]
	v_mfma_f32_16x16x32_bf16 v[82:85], v[166:169], v[220:223], v[82:85]
	s_setprio 0
	s_setprio 1
	v_mfma_f32_16x16x32_bf16 v[110:113], v[170:173], v[192:195], v[110:113]
	v_mfma_f32_16x16x32_bf16 v[102:105], v[178:181], v[192:195], v[102:105]
	v_mfma_f32_16x16x32_bf16 v[94:97], v[170:173], v[200:203], v[94:97]
	v_mfma_f32_16x16x32_bf16 v[86:89], v[178:181], v[200:203], v[86:89]
	v_mfma_f32_16x16x32_bf16 v[78:81], v[170:173], v[208:211], v[78:81]
	v_mfma_f32_16x16x32_bf16 v[74:77], v[178:181], v[208:211], v[74:77]
	v_mfma_f32_16x16x32_bf16 v[70:73], v[170:173], v[216:219], v[70:73]
	v_mfma_f32_16x16x32_bf16 v[66:69], v[178:181], v[216:219], v[66:69]
	v_mfma_f32_16x16x32_bf16 v[110:113], v[174:177], v[196:199], v[110:113]
	v_mfma_f32_16x16x32_bf16 v[102:105], v[188:191], v[196:199], v[102:105]
	v_mfma_f32_16x16x32_bf16 v[94:97], v[174:177], v[204:207], v[94:97]
	v_mfma_f32_16x16x32_bf16 v[86:89], v[188:191], v[204:207], v[86:89]
	v_mfma_f32_16x16x32_bf16 v[78:81], v[174:177], v[212:215], v[78:81]
	v_mfma_f32_16x16x32_bf16 v[74:77], v[188:191], v[212:215], v[74:77]
	v_mfma_f32_16x16x32_bf16 v[70:73], v[174:177], v[220:223], v[70:73]
	v_mfma_f32_16x16x32_bf16 v[66:69], v[188:191], v[220:223], v[66:69]
	s_setprio 0
	s_barrier
; #define PG8_STAGE(bufoff, gbase) do { _Pragma("unroll") for (int _i = 0; _i < 2; ++_i) \
;         __builtin_amdgcn_global_load_lds((const unsigned*)((const char*)(gbase) + voff[_i]), (LAS unsigned*)(lds + (bufoff) + ldsw + _i * 8192), 16, 0, 0); } while (0)
; #define PG8_LDA(dst, b, h) do { _Pragma("unroll") for (int m = 0; m < 4; ++m) _Pragma("unroll") for (int k = 0; k < 2; ++k) dst[m][k] = *(const LAS bf16x8*)(lds + PG8_SA(b, h) + aoff + m * 2048 + k * 1024); } while (0)
; #define PG8_MMA(ai, bj, At, Bt) do { __builtin_amdgcn_s_setprio(1); _Pragma("unroll") for (int m = 0; m < 4; ++m) _Pragma("unroll") for (int n = 0; n < 2; ++n) _Pragma("unroll") for (int k = 0; k < 2; ++k) \
;         acc[ai][bj][m][n] = __builtin_amdgcn_mfma_f32_16x16x32_bf16(Bt[n][k], At[m][k], acc[ai][bj][m][n], 0, 0, 0); __builtin_amdgcn_s_setprio(0); } while (0)
; #define PG8_WAIT_V(n) asm volatile("s_waitcnt vmcnt(" #n ")" ::: "memory")
; #define PG8_WAIT_L(n) asm volatile("s_waitcnt lgkmcnt(" #n ")" ::: "memory")
; #define PG8_BAR __builtin_amdgcn_s_barrier()
; #define PG8_SCHED __builtin_amdgcn_sched_barrier(0)
; template <int EPI> ...
;     ...
;             PG8_LDA(At, 1, 1); PG8_STAGE(PG8_SB(1, 0), b3); PG8_STAGE(PG8_SB(1, 1), b3 + hstep); PG8_STAGE(PG8_SA(1, 0), a3);
;             PG8_WAIT_V(8); PG8_WAIT_L(0); PG8_BAR; PG8_MMA(1, 0, At, B0); PG8_MMA(1, 1, At, B1); PG8_BAR; PG8_SCHED;
;         }
;         if (wr == 0) PG8_BAR;
;         if (SPLIT && cur_slice >= 0) {
	s_add_i32 s30, s62, s40
	v_lshl_add_u64 v[224:225], v[224:225], 0, s[10:11]
	s_mov_b32 m0, s30
	s_nop 0
	global_load_lds_dwordx4 v[224:225], off
	s_add_i32 m0, s30, 0x2000
	s_add_u32 s28, s28, 0x20080
	v_lshl_add_u64 v[224:225], v[226:227], 0, s[10:11]
	s_addc_u32 s29, s29, 0
	s_add_i32 s30, s64, s40
	global_load_lds_dwordx4 v[224:225], off
	v_lshl_add_u64 v[224:225], s[28:29], 0, v[130:131]
	s_mov_b32 m0, s30
	s_nop 0
	global_load_lds_dwordx4 v[224:225], off
	v_lshl_add_u64 v[224:225], s[28:29], 0, v[132:133]
	s_add_i32 m0, s30, 0x2000
	s_nop 0
	global_load_lds_dwordx4 v[224:225], off
	v_lshl_add_u64 v[224:225], v[228:229], 0, s[10:11]
	s_mov_b32 m0, s45
	s_nop 0
	global_load_lds_dwordx4 v[224:225], off
	v_lshl_add_u64 v[224:225], v[230:231], 0, s[10:11]
	s_mov_b32 m0, s46
	s_nop 0
	global_load_lds_dwordx4 v[224:225], off
	ds_read_b128 v[192:195], v160 offset:49152
	ds_read_b128 v[196:199], v160 offset:50176
	ds_read_b128 v[200:203], v160 offset:51200
	ds_read_b128 v[204:207], v160 offset:52224
	ds_read_b128 v[208:211], v160 offset:53248
	ds_read_b128 v[212:215], v160 offset:54272
	ds_read_b128 v[216:219], v160 offset:55296
	ds_read_b128 v[220:223], v160 offset:56320
	s_waitcnt vmcnt(8)
	s_waitcnt lgkmcnt(0)
	s_barrier
	s_setprio 1
	s_waitcnt lgkmcnt(0)
	v_mfma_f32_16x16x32_bf16 v[62:65], v[142:145], v[192:195], v[62:65]
	v_mfma_f32_16x16x32_bf16 v[58:61], v[162:165], v[192:195], v[58:61]
	v_mfma_f32_16x16x32_bf16 v[54:57], v[142:145], v[200:203], v[54:57]
	v_mfma_f32_16x16x32_bf16 v[50:53], v[162:165], v[200:203], v[50:53]
	v_mfma_f32_16x16x32_bf16 v[42:45], v[142:145], v[208:211], v[42:45]
	v_mfma_f32_16x16x32_bf16 v[34:37], v[162:165], v[208:211], v[34:37]
	v_mfma_f32_16x16x32_bf16 v[26:29], v[142:145], v[216:219], v[26:29]
	v_mfma_f32_16x16x32_bf16 v[18:21], v[162:165], v[216:219], v[18:21]
	v_mfma_f32_16x16x32_bf16 v[62:65], v[146:149], v[196:199], v[62:65]
	v_mfma_f32_16x16x32_bf16 v[58:61], v[166:169], v[196:199], v[58:61]
	v_mfma_f32_16x16x32_bf16 v[54:57], v[146:149], v[204:207], v[54:57]
	v_mfma_f32_16x16x32_bf16 v[50:53], v[166:169], v[204:207], v[50:53]
	v_mfma_f32_16x16x32_bf16 v[42:45], v[146:149], v[212:215], v[42:45]
	v_mfma_f32_16x16x32_bf16 v[34:37], v[166:169], v[212:215], v[34:37]
	v_mfma_f32_16x16x32_bf16 v[26:29], v[146:149], v[220:223], v[26:29]
	v_mfma_f32_16x16x32_bf16 v[18:21], v[166:169], v[220:223], v[18:21]
	s_setprio 0
	s_setprio 1
	v_mfma_f32_16x16x32_bf16 v[46:49], v[170:173], v[192:195], v[46:49]
	v_mfma_f32_16x16x32_bf16 v[38:41], v[178:181], v[192:195], v[38:41]
	v_mfma_f32_16x16x32_bf16 v[30:33], v[170:173], v[200:203], v[30:33]
	v_mfma_f32_16x16x32_bf16 v[22:25], v[178:181], v[200:203], v[22:25]
	v_mfma_f32_16x16x32_bf16 v[14:17], v[170:173], v[208:211], v[14:17]
	v_mfma_f32_16x16x32_bf16 v[10:13], v[178:181], v[208:211], v[10:13]
	v_mfma_f32_16x16x32_bf16 v[6:9], v[170:173], v[216:219], v[6:9]
	v_mfma_f32_16x16x32_bf16 v[2:5], v[178:181], v[216:219], v[2:5]
	v_mfma_f32_16x16x32_bf16 v[46:49], v[174:177], v[196:199], v[46:49]
	v_mfma_f32_16x16x32_bf16 v[38:41], v[188:191], v[196:199], v[38:41]
	v_mfma_f32_16x16x32_bf16 v[30:33], v[174:177], v[204:207], v[30:33]
	v_mfma_f32_16x16x32_bf16 v[22:25], v[188:191], v[204:207], v[22:25]
	v_mfma_f32_16x16x32_bf16 v[14:17], v[174:177], v[212:215], v[14:17]
	v_mfma_f32_16x16x32_bf16 v[10:13], v[188:191], v[212:215], v[10:13]
	v_mfma_f32_16x16x32_bf16 v[6:9], v[174:177], v[220:223], v[6:9]
	v_mfma_f32_16x16x32_bf16 v[2:5], v[188:191], v[220:223], v[2:5]
	s_setprio 0
	s_barrier
	s_add_u32 s26, s26, 0x100
	s_addc_u32 s27, s27, 0
	s_add_u32 s60, s60, 0x100
	s_addc_u32 s61, s61, 0
	s_cmp_ge_u32 s63, s57
	s_mov_b32 s62, s63
	s_cbranch_scc0 .LBB0_656
	s_and_b64 vcc, exec, s[12:13]
	s_cbranch_vccz .LBB0_661
	s_barrier
	s_cmp_lt_i32 s0, 0
	s_mov_b64 s[26:27], -1
	s_cbranch_scc1 .LBB0_662

; #define PG8_STAGE(bufoff, gbase) do { _Pragma("unroll") for (int _i = 0; _i < 2; ++_i) \
;         __builtin_amdgcn_global_load_lds((const unsigned*)((const char*)(gbase) + voff[_i]), (LAS unsigned*)(lds + (bufoff) + ldsw + _i * 8192), 16, 0, 0); } while (0)
; #define PG8_LDA(dst, b, h) do { _Pragma("unroll") for (int m = 0; m < 4; ++m) _Pragma("unroll") for (int k = 0; k < 2; ++k) dst[m][k] = *(const LAS bf16x8*)(lds + PG8_SA(b, h) + aoff + m * 2048 + k * 1024); } while (0)
; #define PG8_LDB(dst, b, h) do { _Pragma("unroll") for (int n = 0; n < 2; ++n) _Pragma("unroll") for (int k = 0; k < 2; ++k) dst[n][k] = *(const LAS bf16x8*)(lds + PG8_SB(b, h) + boff + n * 2048 + k * 1024); } while (0)
; #define PG8_MMA(ai, bj, At, Bt) do { __builtin_amdgcn_s_setprio(1); _Pragma("unroll") for (int m = 0; m < 4; ++m) _Pragma("unroll") for (int n = 0; n < 2; ++n) _Pragma("unroll") for (int k = 0; k < 2; ++k) \
;         acc[ai][bj][m][n] = __builtin_amdgcn_mfma_f32_16x16x32_bf16(Bt[n][k], At[m][k], acc[ai][bj][m][n], 0, 0, 0); __builtin_amdgcn_s_setprio(0); } while (0)
; #define PG8_WAIT_V(n) asm volatile("s_waitcnt vmcnt(" #n ")" ::: "memory")
; #define PG8_WAIT_L(n) asm volatile("s_waitcnt lgkmcnt(" #n ")" ::: "memory")
; #define PG8_BAR __builtin_amdgcn_s_barrier()
; #define PG8_SCHED __builtin_amdgcn_sched_barrier(0)
; template <int EPI> ...
;     ...
;             PG8_LDB(B0, 0, 0); PG8_LDB(B1, 0, 1); PG8_SCHED; PG8_LDA(At, 0, 0); PG8_STAGE(PG8_SA(1, 1), a1 + hstep);
;             PG8_WAIT_V(8); PG8_WAIT_L(0); PG8_BAR; PG8_MMA(0, 0, At, B0); PG8_MMA(0, 1, At, B1); PG8_BAR; PG8_SCHED;
;             PG8_LDA(At, 0, 1); PG8_STAGE(PG8_SB(0, 0), b2); PG8_STAGE(PG8_SB(0, 1), b2 + hstep); PG8_STAGE(PG8_SA(0, 0), a2);
;             PG8_WAIT_V(8); PG8_WAIT_L(0); PG8_BAR; PG8_MMA(1, 0, At, B0); PG8_MMA(1, 1, At, B1); PG8_BAR; PG8_SCHED;
.LBB0_737:
	s_add_u32 s26, s24, 0xfffe0080
	s_addc_u32 s27, s25, -1
	s_cmp_eq_u32 s52, 4
	s_cselect_b32 s29, s17, s27
	s_cselect_b32 s28, s48, s26
	s_cselect_b32 s27, s15, s51
	s_cselect_b32 s26, s49, s50
	v_lshl_add_u64 v[180:181], s[24:25], 0, v[134:135]
	s_add_i32 m0, s23, 0xc000
	s_nop 0
	global_load_lds_dwordx4 v[180:181], off
	v_lshl_add_u64 v[180:181], s[24:25], 0, v[136:137]
	s_add_i32 m0, s23, 0xe000
	s_nop 0
	global_load_lds_dwordx4 v[180:181], off
	ds_read_b128 v[142:145], v153
	ds_read_b128 v[146:149], v153 offset:1024
	ds_read_b128 v[156:159], v153 offset:2048
	ds_read_b128 v[160:163], v153 offset:3072
	ds_read_b128 v[164:167], v154
	ds_read_b128 v[168:171], v154 offset:1024
	ds_read_b128 v[172:175], v154 offset:2048
	ds_read_b128 v[176:179], v154 offset:3072
	ds_read_b128 v[188:191], v155
	ds_read_b128 v[192:195], v155 offset:1024
	ds_read_b128 v[196:199], v155 offset:2048
	ds_read_b128 v[200:203], v155 offset:3072
	ds_read_b128 v[204:207], v155 offset:4096
	ds_read_b128 v[208:211], v155 offset:5120
	ds_read_b128 v[212:215], v155 offset:6144
	ds_read_b128 v[216:219], v155 offset:7168
	s_waitcnt vmcnt(8)
	s_waitcnt lgkmcnt(0)
	s_barrier
	s_setprio 1
	s_waitcnt lgkmcnt(0)
	v_mfma_f32_16x16x32_bf16 v[126:129], v[142:145], v[188:191], v[126:129]
	v_mfma_f32_16x16x32_bf16 v[122:125], v[156:159], v[188:191], v[122:125]
	v_mfma_f32_16x16x32_bf16 v[110:113], v[142:145], v[196:199], v[110:113]
	v_mfma_f32_16x16x32_bf16 v[106:109], v[156:159], v[196:199], v[106:109]
	v_mfma_f32_16x16x32_bf16 v[94:97], v[142:145], v[204:207], v[94:97]
	v_mfma_f32_16x16x32_bf16 v[90:93], v[156:159], v[204:207], v[90:93]
	v_mfma_f32_16x16x32_bf16 v[78:81], v[142:145], v[212:215], v[78:81]
	v_mfma_f32_16x16x32_bf16 v[74:77], v[156:159], v[212:215], v[74:77]
	v_mfma_f32_16x16x32_bf16 v[126:129], v[146:149], v[192:195], v[126:129]
	v_mfma_f32_16x16x32_bf16 v[122:125], v[160:163], v[192:195], v[122:125]
	v_mfma_f32_16x16x32_bf16 v[110:113], v[146:149], v[200:203], v[110:113]
	v_mfma_f32_16x16x32_bf16 v[106:109], v[160:163], v[200:203], v[106:109]
	v_mfma_f32_16x16x32_bf16 v[94:97], v[146:149], v[208:211], v[94:97]
	v_mfma_f32_16x16x32_bf16 v[90:93], v[160:163], v[208:211], v[90:93]
	v_mfma_f32_16x16x32_bf16 v[78:81], v[146:149], v[216:219], v[78:81]
	v_mfma_f32_16x16x32_bf16 v[74:77], v[160:163], v[216:219], v[74:77]
	s_setprio 0
	s_setprio 1
	v_mfma_f32_16x16x32_bf16 v[118:121], v[164:167], v[188:191], v[118:121]
	v_mfma_f32_16x16x32_bf16 v[114:117], v[172:175], v[188:191], v[114:117]
	v_mfma_f32_16x16x32_bf16 v[102:105], v[164:167], v[196:199], v[102:105]
	v_mfma_f32_16x16x32_bf16 v[98:101], v[172:175], v[196:199], v[98:101]
	v_mfma_f32_16x16x32_bf16 v[86:89], v[164:167], v[204:207], v[86:89]
	v_mfma_f32_16x16x32_bf16 v[82:85], v[172:175], v[204:207], v[82:85]
	v_mfma_f32_16x16x32_bf16 v[70:73], v[164:167], v[212:215], v[70:73]
	v_mfma_f32_16x16x32_bf16 v[66:69], v[172:175], v[212:215], v[66:69]
	v_mfma_f32_16x16x32_bf16 v[118:121], v[168:171], v[192:195], v[118:121]
	v_mfma_f32_16x16x32_bf16 v[114:117], v[176:179], v[192:195], v[114:117]
	v_mfma_f32_16x16x32_bf16 v[102:105], v[168:171], v[200:203], v[102:105]
	v_mfma_f32_16x16x32_bf16 v[98:101], v[176:179], v[200:203], v[98:101]
	v_mfma_f32_16x16x32_bf16 v[86:89], v[168:171], v[208:211], v[86:89]
	v_mfma_f32_16x16x32_bf16 v[82:85], v[176:179], v[208:211], v[82:85]
	v_mfma_f32_16x16x32_bf16 v[70:73], v[168:171], v[216:219], v[70:73]
	v_mfma_f32_16x16x32_bf16 v[66:69], v[176:179], v[216:219], v[66:69]
	s_setprio 0
	s_barrier
	s_add_i32 s53, s44, s30
	v_lshl_add_u64 v[180:181], s[26:27], 0, v[130:131]
	s_mov_b32 m0, s53
	s_nop 0
	global_load_lds_dwordx4 v[180:181], off
	s_add_i32 m0, s53, 0x2000
	s_add_u32 s54, s26, 0x20000
	v_lshl_add_u64 v[220:221], s[26:27], 0, v[132:133]
	s_addc_u32 s55, s27, 0
	s_add_i32 s53, s45, s30
	global_load_lds_dwordx4 v[220:221], off
	v_lshl_add_u64 v[222:223], s[54:55], 0, v[130:131]
	s_mov_b32 m0, s53
	v_lshl_add_u64 v[224:225], s[28:29], 0, v[132:133]
	global_load_lds_dwordx4 v[222:223], off
	v_lshl_add_u64 v[222:223], s[54:55], 0, v[132:133]
	s_add_i32 m0, s53, 0x2000
	s_nop 0
	global_load_lds_dwordx4 v[222:223], off
	v_lshl_add_u64 v[222:223], s[28:29], 0, v[130:131]
	s_mov_b32 m0, s23
	s_nop 0
	global_load_lds_dwordx4 v[222:223], off
	s_mov_b32 m0, s31
	s_nop 0
	global_load_lds_dwordx4 v[224:225], off
	ds_read_b128 v[188:191], v155 offset:16384
	ds_read_b128 v[192:195], v155 offset:17408
	ds_read_b128 v[196:199], v155 offset:18432
	ds_read_b128 v[200:203], v155 offset:19456
	ds_read_b128 v[204:207], v155 offset:20480
	ds_read_b128 v[208:211], v155 offset:21504
	ds_read_b128 v[212:215], v155 offset:22528
	ds_read_b128 v[216:219], v155 offset:23552
	s_waitcnt vmcnt(8)
	s_waitcnt lgkmcnt(0)
	s_barrier
; #define PG8_STAGE(bufoff, gbase) do { _Pragma("unroll") for (int _i = 0; _i < 2; ++_i) \
;         __builtin_amdgcn_global_load_lds((const unsigned*)((const char*)(gbase) + voff[_i]), (LAS unsigned*)(lds + (bufoff) + ldsw + _i * 8192), 16, 0, 0); } while (0)
; #define PG8_LDA(dst, b, h) do { _Pragma("unroll") for (int m = 0; m < 4; ++m) _Pragma("unroll") for (int k = 0; k < 2; ++k) dst[m][k] = *(const LAS bf16x8*)(lds + PG8_SA(b, h) + aoff + m * 2048 + k * 1024); } while (0)
; #define PG8_LDB(dst, b, h) do { _Pragma("unroll") for (int n = 0; n < 2; ++n) _Pragma("unroll") for (int k = 0; k < 2; ++k) dst[n][k] = *(const LAS bf16x8*)(lds + PG8_SB(b, h) + boff + n * 2048 + k * 1024); } while (0)
; #define PG8_MMA(ai, bj, At, Bt) do { __builtin_amdgcn_s_setprio(1); _Pragma("unroll") for (int m = 0; m < 4; ++m) _Pragma("unroll") for (int n = 0; n < 2; ++n) _Pragma("unroll") for (int k = 0; k < 2; ++k) \
;         acc[ai][bj][m][n] = __builtin_amdgcn_mfma_f32_16x16x32_bf16(Bt[n][k], At[m][k], acc[ai][bj][m][n], 0, 0, 0); __builtin_amdgcn_s_setprio(0); } while (0)
; #define PG8_WAIT_V(n) asm volatile("s_waitcnt vmcnt(" #n ")" ::: "memory")
; #define PG8_WAIT_L(n) asm volatile("s_waitcnt lgkmcnt(" #n ")" ::: "memory")
; #define PG8_BAR __builtin_amdgcn_s_barrier()
; #define PG8_SCHED __builtin_amdgcn_sched_barrier(0)
; template <int EPI> ...
;     ...
;             PG8_WAIT_V(8); PG8_WAIT_L(0); PG8_BAR; PG8_MMA(1, 0, At, B0); PG8_MMA(1, 1, At, B1); PG8_BAR; PG8_SCHED;
;             PG8_LDB(B0, 1, 0); PG8_LDB(B1, 1, 1); PG8_SCHED; PG8_LDA(At, 1, 0); PG8_STAGE(PG8_SA(0, 1), a2 + hstep);
;             PG8_WAIT_V(8); PG8_WAIT_L(0); PG8_BAR; PG8_MMA(0, 0, At, B0); PG8_MMA(0, 1, At, B1); PG8_BAR; PG8_SCHED;
	s_setprio 1
	s_waitcnt lgkmcnt(0)
	v_mfma_f32_16x16x32_bf16 v[62:65], v[142:145], v[188:191], v[62:65]
	v_mfma_f32_16x16x32_bf16 v[58:61], v[156:159], v[188:191], v[58:61]
	v_mfma_f32_16x16x32_bf16 v[46:49], v[142:145], v[196:199], v[46:49]
	v_mfma_f32_16x16x32_bf16 v[42:45], v[156:159], v[196:199], v[42:45]
	v_mfma_f32_16x16x32_bf16 v[30:33], v[142:145], v[204:207], v[30:33]
	v_mfma_f32_16x16x32_bf16 v[26:29], v[156:159], v[204:207], v[26:29]
	v_mfma_f32_16x16x32_bf16 v[14:17], v[142:145], v[212:215], v[14:17]
	v_mfma_f32_16x16x32_bf16 v[10:13], v[156:159], v[212:215], v[10:13]
	v_mfma_f32_16x16x32_bf16 v[62:65], v[146:149], v[192:195], v[62:65]
	v_mfma_f32_16x16x32_bf16 v[58:61], v[160:163], v[192:195], v[58:61]
	v_mfma_f32_16x16x32_bf16 v[46:49], v[146:149], v[200:203], v[46:49]
	v_mfma_f32_16x16x32_bf16 v[42:45], v[160:163], v[200:203], v[42:45]
	v_mfma_f32_16x16x32_bf16 v[30:33], v[146:149], v[208:211], v[30:33]
	v_mfma_f32_16x16x32_bf16 v[26:29], v[160:163], v[208:211], v[26:29]
	v_mfma_f32_16x16x32_bf16 v[14:17], v[146:149], v[216:219], v[14:17]
	v_mfma_f32_16x16x32_bf16 v[10:13], v[160:163], v[216:219], v[10:13]
	s_setprio 0
	s_setprio 1
	v_mfma_f32_16x16x32_bf16 v[54:57], v[164:167], v[188:191], v[54:57]
	v_mfma_f32_16x16x32_bf16 v[50:53], v[172:175], v[188:191], v[50:53]
	v_mfma_f32_16x16x32_bf16 v[38:41], v[164:167], v[196:199], v[38:41]
	v_mfma_f32_16x16x32_bf16 v[34:37], v[172:175], v[196:199], v[34:37]
	v_mfma_f32_16x16x32_bf16 v[22:25], v[164:167], v[204:207], v[22:25]
	v_mfma_f32_16x16x32_bf16 v[18:21], v[172:175], v[204:207], v[18:21]
	v_mfma_f32_16x16x32_bf16 v[6:9], v[164:167], v[212:215], v[6:9]
	v_mfma_f32_16x16x32_bf16 v[2:5], v[172:175], v[212:215], v[2:5]
	v_mfma_f32_16x16x32_bf16 v[54:57], v[168:171], v[192:195], v[54:57]
	v_mfma_f32_16x16x32_bf16 v[50:53], v[176:179], v[192:195], v[50:53]
	v_mfma_f32_16x16x32_bf16 v[38:41], v[168:171], v[200:203], v[38:41]
	v_mfma_f32_16x16x32_bf16 v[34:37], v[176:179], v[200:203], v[34:37]
	v_mfma_f32_16x16x32_bf16 v[22:25], v[168:171], v[208:211], v[22:25]
	v_mfma_f32_16x16x32_bf16 v[18:21], v[176:179], v[208:211], v[18:21]
	v_mfma_f32_16x16x32_bf16 v[6:9], v[168:171], v[216:219], v[6:9]
	v_mfma_f32_16x16x32_bf16 v[2:5], v[176:179], v[216:219], v[2:5]
	s_setprio 0
	s_barrier
	s_add_i32 s53, 0, 0x18000
	s_add_i32 s54, 0, 0x1c000
	s_add_u32 s28, s28, 0x20000
	s_addc_u32 s29, s29, 0
	s_mov_b32 m0, s38
	v_lshl_add_u64 v[226:227], s[28:29], 0, v[130:131]
	global_load_lds_dwordx4 v[226:227], off
	v_lshl_add_u64 v[226:227], s[28:29], 0, v[132:133]
	s_mov_b32 m0, s39
	s_nop 0
	global_load_lds_dwordx4 v[226:227], off
	v_add_u32_e32 v160, s53, v151
	v_add_u32_e32 v176, s54, v151
	ds_read_b128 v[142:145], v160
	ds_read_b128 v[146:149], v160 offset:1024
	ds_read_b128 v[156:159], v160 offset:2048
	ds_read_b128 v[160:163], v160 offset:3072
	ds_read_b128 v[164:167], v176
	ds_read_b128 v[168:171], v176 offset:1024
	ds_read_b128 v[172:175], v176 offset:2048
	ds_read_b128 v[176:179], v176 offset:3072
	ds_read_b128 v[188:191], v155 offset:32768
	ds_read_b128 v[192:195], v155 offset:33792
	ds_read_b128 v[196:199], v155 offset:34816
	ds_read_b128 v[200:203], v155 offset:35840
	ds_read_b128 v[204:207], v155 offset:36864
	ds_read_b128 v[208:211], v155 offset:37888
	ds_read_b128 v[212:215], v155 offset:38912
	ds_read_b128 v[216:219], v155 offset:39936
	s_waitcnt vmcnt(8)
	s_waitcnt lgkmcnt(0)
	s_barrier
	s_setprio 1
	s_waitcnt lgkmcnt(0)
	v_mfma_f32_16x16x32_bf16 v[126:129], v[142:145], v[188:191], v[126:129]
	v_mfma_f32_16x16x32_bf16 v[122:125], v[156:159], v[188:191], v[122:125]
	v_mfma_f32_16x16x32_bf16 v[110:113], v[142:145], v[196:199], v[110:113]
	v_mfma_f32_16x16x32_bf16 v[106:109], v[156:159], v[196:199], v[106:109]
	v_mfma_f32_16x16x32_bf16 v[94:97], v[142:145], v[204:207], v[94:97]
	v_mfma_f32_16x16x32_bf16 v[90:93], v[156:159], v[204:207], v[90:93]
	v_mfma_f32_16x16x32_bf16 v[78:81], v[142:145], v[212:215], v[78:81]
	v_mfma_f32_16x16x32_bf16 v[74:77], v[156:159], v[212:215], v[74:77]
	v_mfma_f32_16x16x32_bf16 v[126:129], v[146:149], v[192:195], v[126:129]
	v_mfma_f32_16x16x32_bf16 v[122:125], v[160:163], v[192:195], v[122:125]
	v_mfma_f32_16x16x32_bf16 v[110:113], v[146:149], v[200:203], v[110:113]
	v_mfma_f32_16x16x32_bf16 v[106:109], v[160:163], v[200:203], v[106:109]
	v_mfma_f32_16x16x32_bf16 v[94:97], v[146:149], v[208:211], v[94:97]
	v_mfma_f32_16x16x32_bf16 v[90:93], v[160:163], v[208:211], v[90:93]
	v_mfma_f32_16x16x32_bf16 v[78:81], v[146:149], v[216:219], v[78:81]
	v_mfma_f32_16x16x32_bf16 v[74:77], v[160:163], v[216:219], v[74:77]
	s_setprio 0
	s_setprio 1
	v_mfma_f32_16x16x32_bf16 v[118:121], v[164:167], v[188:191], v[118:121]
	v_mfma_f32_16x16x32_bf16 v[114:117], v[172:175], v[188:191], v[114:117]
	v_mfma_f32_16x16x32_bf16 v[102:105], v[164:167], v[196:199], v[102:105]
	v_mfma_f32_16x16x32_bf16 v[98:101], v[172:175], v[196:199], v[98:101]
	v_mfma_f32_16x16x32_bf16 v[86:89], v[164:167], v[204:207], v[86:89]
	v_mfma_f32_16x16x32_bf16 v[82:85], v[172:175], v[204:207], v[82:85]
	v_mfma_f32_16x16x32_bf16 v[70:73], v[164:167], v[212:215], v[70:73]
	v_mfma_f32_16x16x32_bf16 v[66:69], v[172:175], v[212:215], v[66:69]
	v_mfma_f32_16x16x32_bf16 v[118:121], v[168:171], v[192:195], v[118:121]
	v_mfma_f32_16x16x32_bf16 v[114:117], v[176:179], v[192:195], v[114:117]
	v_mfma_f32_16x16x32_bf16 v[102:105], v[168:171], v[200:203], v[102:105]
	v_mfma_f32_16x16x32_bf16 v[98:101], v[176:179], v[200:203], v[98:101]
	v_mfma_f32_16x16x32_bf16 v[86:89], v[168:171], v[208:211], v[86:89]
	v_mfma_f32_16x16x32_bf16 v[82:85], v[176:179], v[208:211], v[82:85]
	v_mfma_f32_16x16x32_bf16 v[70:73], v[168:171], v[216:219], v[70:73]
	v_mfma_f32_16x16x32_bf16 v[66:69], v[176:179], v[216:219], v[66:69]
	s_setprio 0
	s_barrier
; #define PG8_STAGE(bufoff, gbase) do { _Pragma("unroll") for (int _i = 0; _i < 2; ++_i) \
;         __builtin_amdgcn_global_load_lds((const unsigned*)((const char*)(gbase) + voff[_i]), (LAS unsigned*)(lds + (bufoff) + ldsw + _i * 8192), 16, 0, 0); } while (0)
; #define PG8_LDA(dst, b, h) do { _Pragma("unroll") for (int m = 0; m < 4; ++m) _Pragma("unroll") for (int k = 0; k < 2; ++k) dst[m][k] = *(const LAS bf16x8*)(lds + PG8_SA(b, h) + aoff + m * 2048 + k * 1024); } while (0)
; #define PG8_MMA(ai, bj, At, Bt) do { __builtin_amdgcn_s_setprio(1); _Pragma("unroll") for (int m = 0; m < 4; ++m) _Pragma("unroll") for (int n = 0; n < 2; ++n) _Pragma("unroll") for (int k = 0; k < 2; ++k) \
;         acc[ai][bj][m][n] = __builtin_amdgcn_mfma_f32_16x16x32_bf16(Bt[n][k], At[m][k], acc[ai][bj][m][n], 0, 0, 0); __builtin_amdgcn_s_setprio(0); } while (0)
; #define PG8_WAIT_V(n) asm volatile("s_waitcnt vmcnt(" #n ")" ::: "memory")
; #define PG8_WAIT_L(n) asm volatile("s_waitcnt lgkmcnt(" #n ")" ::: "memory")
; #define PG8_BAR __builtin_amdgcn_s_barrier()
; #define PG8_SCHED __builtin_amdgcn_sched_barrier(0)
; template <int EPI> ...
;     ...
;             PG8_LDA(At, 1, 1); PG8_STAGE(PG8_SB(1, 0), b3); PG8_STAGE(PG8_SB(1, 1), b3 + hstep); PG8_STAGE(PG8_SA(1, 0), a3);
;             PG8_WAIT_V(8); PG8_WAIT_L(0); PG8_BAR; PG8_MMA(1, 0, At, B0); PG8_MMA(1, 1, At, B1); PG8_BAR; PG8_SCHED;
;         }
;         if (wr == 0) PG8_BAR;
;         if (SPLIT && cur_slice >= 0) {
	s_add_i32 s28, s53, s30
	v_lshl_add_u64 v[180:181], v[180:181], 0, s[6:7]
	s_mov_b32 m0, s28
	s_nop 0
	global_load_lds_dwordx4 v[180:181], off
	s_add_i32 m0, s28, 0x2000
	s_add_u32 s26, s26, 0x20080
	v_lshl_add_u64 v[180:181], v[220:221], 0, s[6:7]
	s_addc_u32 s27, s27, 0
	s_add_i32 s28, s54, s30
	global_load_lds_dwordx4 v[180:181], off
	v_lshl_add_u64 v[180:181], s[26:27], 0, v[130:131]
	s_mov_b32 m0, s28
	s_nop 0
	global_load_lds_dwordx4 v[180:181], off
	v_lshl_add_u64 v[180:181], s[26:27], 0, v[132:133]
	s_add_i32 m0, s28, 0x2000
	s_nop 0
	global_load_lds_dwordx4 v[180:181], off
	v_lshl_add_u64 v[180:181], v[222:223], 0, s[6:7]
	s_mov_b32 m0, s41
	s_nop 0
	global_load_lds_dwordx4 v[180:181], off
	v_lshl_add_u64 v[180:181], v[224:225], 0, s[6:7]
	s_mov_b32 m0, s42
	s_nop 0
	global_load_lds_dwordx4 v[180:181], off
	ds_read_b128 v[188:191], v155 offset:49152
	ds_read_b128 v[192:195], v155 offset:50176
	ds_read_b128 v[196:199], v155 offset:51200
	ds_read_b128 v[200:203], v155 offset:52224
	ds_read_b128 v[204:207], v155 offset:53248
	ds_read_b128 v[208:211], v155 offset:54272
	ds_read_b128 v[212:215], v155 offset:55296
	ds_read_b128 v[216:219], v155 offset:56320
	s_waitcnt vmcnt(8)
	s_waitcnt lgkmcnt(0)
	s_barrier
	s_setprio 1
	s_waitcnt lgkmcnt(0)
	v_mfma_f32_16x16x32_bf16 v[62:65], v[142:145], v[188:191], v[62:65]
	v_mfma_f32_16x16x32_bf16 v[58:61], v[156:159], v[188:191], v[58:61]
	v_mfma_f32_16x16x32_bf16 v[46:49], v[142:145], v[196:199], v[46:49]
	v_mfma_f32_16x16x32_bf16 v[42:45], v[156:159], v[196:199], v[42:45]
	v_mfma_f32_16x16x32_bf16 v[30:33], v[142:145], v[204:207], v[30:33]
	v_mfma_f32_16x16x32_bf16 v[26:29], v[156:159], v[204:207], v[26:29]
	v_mfma_f32_16x16x32_bf16 v[14:17], v[142:145], v[212:215], v[14:17]
	v_mfma_f32_16x16x32_bf16 v[10:13], v[156:159], v[212:215], v[10:13]
	v_mfma_f32_16x16x32_bf16 v[62:65], v[146:149], v[192:195], v[62:65]
	v_mfma_f32_16x16x32_bf16 v[58:61], v[160:163], v[192:195], v[58:61]
	v_mfma_f32_16x16x32_bf16 v[46:49], v[146:149], v[200:203], v[46:49]
	v_mfma_f32_16x16x32_bf16 v[42:45], v[160:163], v[200:203], v[42:45]
	v_mfma_f32_16x16x32_bf16 v[30:33], v[146:149], v[208:211], v[30:33]
	v_mfma_f32_16x16x32_bf16 v[26:29], v[160:163], v[208:211], v[26:29]
	v_mfma_f32_16x16x32_bf16 v[14:17], v[146:149], v[216:219], v[14:17]
	v_mfma_f32_16x16x32_bf16 v[10:13], v[160:163], v[216:219], v[10:13]
	s_setprio 0
	s_setprio 1
	v_mfma_f32_16x16x32_bf16 v[54:57], v[164:167], v[188:191], v[54:57]
	v_mfma_f32_16x16x32_bf16 v[50:53], v[172:175], v[188:191], v[50:53]
	v_mfma_f32_16x16x32_bf16 v[38:41], v[164:167], v[196:199], v[38:41]
	v_mfma_f32_16x16x32_bf16 v[34:37], v[172:175], v[196:199], v[34:37]
	v_mfma_f32_16x16x32_bf16 v[22:25], v[164:167], v[204:207], v[22:25]
	v_mfma_f32_16x16x32_bf16 v[18:21], v[172:175], v[204:207], v[18:21]
	v_mfma_f32_16x16x32_bf16 v[6:9], v[164:167], v[212:215], v[6:9]
	v_mfma_f32_16x16x32_bf16 v[2:5], v[172:175], v[212:215], v[2:5]
	v_mfma_f32_16x16x32_bf16 v[54:57], v[168:171], v[192:195], v[54:57]
	v_mfma_f32_16x16x32_bf16 v[50:53], v[176:179], v[192:195], v[50:53]
	v_mfma_f32_16x16x32_bf16 v[38:41], v[168:171], v[200:203], v[38:41]
	v_mfma_f32_16x16x32_bf16 v[34:37], v[176:179], v[200:203], v[34:37]
	v_mfma_f32_16x16x32_bf16 v[22:25], v[168:171], v[208:211], v[22:25]
	v_mfma_f32_16x16x32_bf16 v[18:21], v[176:179], v[208:211], v[18:21]
	v_mfma_f32_16x16x32_bf16 v[6:9], v[168:171], v[216:219], v[6:9]
	v_mfma_f32_16x16x32_bf16 v[2:5], v[176:179], v[216:219], v[2:5]
	s_setprio 0
	s_barrier
	s_add_i32 s52, s52, 2
	s_add_u32 s24, s24, 0x100
	s_addc_u32 s25, s25, 0
	s_add_u32 s50, s50, 0x100
	s_addc_u32 s51, s51, 0
	s_cmp_gt_u32 s52, 5
	s_cbranch_scc0 .LBB0_737
	s_and_b64 vcc, exec, s[8:9]
	s_cbranch_vccz .LBB0_740
	s_barrier

; #define PG8_STAGE(bufoff, gbase) do { _Pragma("unroll") for (int _i = 0; _i < 2; ++_i) \
;         __builtin_amdgcn_global_load_lds((const unsigned*)((const char*)(gbase) + voff[_i]), (LAS unsigned*)(lds + (bufoff) + ldsw + _i * 8192), 16, 0, 0); } while (0)
; #define PG8_LDA(dst, b, h) do { _Pragma("unroll") for (int m = 0; m < 4; ++m) _Pragma("unroll") for (int k = 0; k < 2; ++k) dst[m][k] = *(const LAS bf16x8*)(lds + PG8_SA(b, h) + aoff + m * 2048 + k * 1024); } while (0)
; #define PG8_LDB(dst, b, h) do { _Pragma("unroll") for (int n = 0; n < 2; ++n) _Pragma("unroll") for (int k = 0; k < 2; ++k) dst[n][k] = *(const LAS bf16x8*)(lds + PG8_SB(b, h) + boff + n * 2048 + k * 1024); } while (0)
; #define PG8_MMA(ai, bj, At, Bt) do { __builtin_amdgcn_s_setprio(1); _Pragma("unroll") for (int m = 0; m < 4; ++m) _Pragma("unroll") for (int n = 0; n < 2; ++n) _Pragma("unroll") for (int k = 0; k < 2; ++k) \
;         acc[ai][bj][m][n] = __builtin_amdgcn_mfma_f32_16x16x32_bf16(Bt[n][k], At[m][k], acc[ai][bj][m][n], 0, 0, 0); __builtin_amdgcn_s_setprio(0); } while (0)
; #define PG8_WAIT_V(n) asm volatile("s_waitcnt vmcnt(" #n ")" ::: "memory")
; #define PG8_WAIT_L(n) asm volatile("s_waitcnt lgkmcnt(" #n ")" ::: "memory")
; #define PG8_BAR __builtin_amdgcn_s_barrier()
; #define PG8_SCHED __builtin_amdgcn_sched_barrier(0)
; template <int EPI> ...
;     ...
;             PG8_LDB(B0, 0, 0); PG8_LDB(B1, 0, 1); PG8_SCHED; PG8_LDA(At, 0, 0); PG8_STAGE(PG8_SA(1, 1), a1 + hstep);
;             PG8_WAIT_V(8); PG8_WAIT_L(0); PG8_BAR; PG8_MMA(0, 0, At, B0); PG8_MMA(0, 1, At, B1); PG8_BAR; PG8_SCHED;
;             PG8_LDA(At, 0, 1); PG8_STAGE(PG8_SB(0, 0), b2); PG8_STAGE(PG8_SB(0, 1), b2 + hstep); PG8_STAGE(PG8_SA(0, 0), a2);
;             PG8_WAIT_V(8); PG8_WAIT_L(0); PG8_BAR; PG8_MMA(1, 0, At, B0); PG8_MMA(1, 1, At, B1); PG8_BAR; PG8_SCHED;
.LBB0_825:
	s_add_i32 s57, s34, 2
	s_add_u32 s35, s30, 0xfffc0080
	s_addc_u32 s36, s31, -1
	s_cmp_eq_u32 s54, s34
	s_cselect_b32 s34, s53, s55
	s_cselect_b32 s37, s5, s36
	s_cselect_b32 s36, s19, s35
	s_cselect_b32 s35, s17, s56
	v_lshl_add_u64 v[146:147], s[30:31], 0, v[136:137]
	s_add_i32 m0, s7, 0xc000
	s_nop 0
	global_load_lds_dwordx4 v[146:147], off
	v_lshl_add_u64 v[146:147], s[30:31], 0, v[138:139]
	s_add_i32 m0, s7, 0xe000
	s_nop 0
	global_load_lds_dwordx4 v[146:147], off
	ds_read_b128 v[142:145], v152
	ds_read_b128 v[156:159], v152 offset:1024
	ds_read_b128 v[160:163], v152 offset:2048
	ds_read_b128 v[164:167], v152 offset:3072
	ds_read_b128 v[168:171], v153
	ds_read_b128 v[172:175], v153 offset:1024
	ds_read_b128 v[176:179], v153 offset:2048
	ds_read_b128 v[188:191], v153 offset:3072
	ds_read_b128 v[192:195], v154
	ds_read_b128 v[196:199], v154 offset:1024
	ds_read_b128 v[200:203], v154 offset:2048
	ds_read_b128 v[204:207], v154 offset:3072
	ds_read_b128 v[208:211], v154 offset:4096
	ds_read_b128 v[212:215], v154 offset:5120
	ds_read_b128 v[216:219], v154 offset:6144
	ds_read_b128 v[220:223], v154 offset:7168
	s_waitcnt vmcnt(8)
	s_waitcnt lgkmcnt(0)
	s_barrier
	s_setprio 1
	s_waitcnt lgkmcnt(0)
	v_mfma_f32_16x16x32_bf16 v[126:129], v[142:145], v[192:195], v[126:129]
	v_mfma_f32_16x16x32_bf16 v[122:125], v[160:163], v[192:195], v[122:125]
	v_mfma_f32_16x16x32_bf16 v[118:121], v[142:145], v[200:203], v[118:121]
	v_mfma_f32_16x16x32_bf16 v[114:117], v[160:163], v[200:203], v[114:117]
	v_mfma_f32_16x16x32_bf16 v[106:109], v[142:145], v[208:211], v[106:109]
	v_mfma_f32_16x16x32_bf16 v[98:101], v[160:163], v[208:211], v[98:101]
	v_mfma_f32_16x16x32_bf16 v[90:93], v[142:145], v[216:219], v[90:93]
	v_mfma_f32_16x16x32_bf16 v[82:85], v[160:163], v[216:219], v[82:85]
	v_mfma_f32_16x16x32_bf16 v[126:129], v[156:159], v[196:199], v[126:129]
	v_mfma_f32_16x16x32_bf16 v[122:125], v[164:167], v[196:199], v[122:125]
	v_mfma_f32_16x16x32_bf16 v[118:121], v[156:159], v[204:207], v[118:121]
	v_mfma_f32_16x16x32_bf16 v[114:117], v[164:167], v[204:207], v[114:117]
	v_mfma_f32_16x16x32_bf16 v[106:109], v[156:159], v[212:215], v[106:109]
	v_mfma_f32_16x16x32_bf16 v[98:101], v[164:167], v[212:215], v[98:101]
	v_mfma_f32_16x16x32_bf16 v[90:93], v[156:159], v[220:223], v[90:93]
	v_mfma_f32_16x16x32_bf16 v[82:85], v[164:167], v[220:223], v[82:85]
	s_setprio 0
	s_setprio 1
	v_mfma_f32_16x16x32_bf16 v[110:113], v[168:171], v[192:195], v[110:113]
	v_mfma_f32_16x16x32_bf16 v[102:105], v[176:179], v[192:195], v[102:105]
	v_mfma_f32_16x16x32_bf16 v[94:97], v[168:171], v[200:203], v[94:97]
	v_mfma_f32_16x16x32_bf16 v[86:89], v[176:179], v[200:203], v[86:89]
	v_mfma_f32_16x16x32_bf16 v[78:81], v[168:171], v[208:211], v[78:81]
	v_mfma_f32_16x16x32_bf16 v[74:77], v[176:179], v[208:211], v[74:77]
	v_mfma_f32_16x16x32_bf16 v[70:73], v[168:171], v[216:219], v[70:73]
	v_mfma_f32_16x16x32_bf16 v[66:69], v[176:179], v[216:219], v[66:69]
	v_mfma_f32_16x16x32_bf16 v[110:113], v[172:175], v[196:199], v[110:113]
	v_mfma_f32_16x16x32_bf16 v[102:105], v[188:191], v[196:199], v[102:105]
	v_mfma_f32_16x16x32_bf16 v[94:97], v[172:175], v[204:207], v[94:97]
	v_mfma_f32_16x16x32_bf16 v[86:89], v[188:191], v[204:207], v[86:89]
	v_mfma_f32_16x16x32_bf16 v[78:81], v[172:175], v[212:215], v[78:81]
	v_mfma_f32_16x16x32_bf16 v[74:77], v[188:191], v[212:215], v[74:77]
	v_mfma_f32_16x16x32_bf16 v[70:73], v[172:175], v[220:223], v[70:73]
	v_mfma_f32_16x16x32_bf16 v[66:69], v[188:191], v[220:223], v[66:69]
	s_setprio 0
	s_barrier
	s_add_i32 s58, s46, s39
	v_lshl_add_u64 v[146:147], s[34:35], 0, v[130:131]
	s_mov_b32 m0, s58
	s_nop 0
	global_load_lds_dwordx4 v[146:147], off
	s_add_i32 m0, s58, 0x2000
	s_add_u32 s58, s34, 0x40000
	v_lshl_add_u64 v[180:181], s[34:35], 0, v[132:133]
	s_addc_u32 s59, s35, 0
	s_add_i32 s60, s47, s39
	global_load_lds_dwordx4 v[180:181], off
	v_lshl_add_u64 v[224:225], s[58:59], 0, v[130:131]
	s_mov_b32 m0, s60
	v_lshl_add_u64 v[226:227], s[36:37], 0, v[132:133]
	global_load_lds_dwordx4 v[224:225], off
	v_lshl_add_u64 v[224:225], s[58:59], 0, v[132:133]
	s_add_i32 m0, s60, 0x2000
	s_nop 0
	global_load_lds_dwordx4 v[224:225], off
	v_lshl_add_u64 v[224:225], s[36:37], 0, v[130:131]
	s_mov_b32 m0, s7
	s_nop 0
	global_load_lds_dwordx4 v[224:225], off
	s_mov_b32 m0, s40
	s_nop 0
	global_load_lds_dwordx4 v[226:227], off
	ds_read_b128 v[192:195], v154 offset:16384
	ds_read_b128 v[196:199], v154 offset:17408
	ds_read_b128 v[200:203], v154 offset:18432
	ds_read_b128 v[204:207], v154 offset:19456
	ds_read_b128 v[208:211], v154 offset:20480
	ds_read_b128 v[212:215], v154 offset:21504
	ds_read_b128 v[216:219], v154 offset:22528
	ds_read_b128 v[220:223], v154 offset:23552
	s_waitcnt vmcnt(8)
	s_waitcnt lgkmcnt(0)
	s_barrier
; #define PG8_STAGE(bufoff, gbase) do { _Pragma("unroll") for (int _i = 0; _i < 2; ++_i) \
;         __builtin_amdgcn_global_load_lds((const unsigned*)((const char*)(gbase) + voff[_i]), (LAS unsigned*)(lds + (bufoff) + ldsw + _i * 8192), 16, 0, 0); } while (0)
; #define PG8_LDA(dst, b, h) do { _Pragma("unroll") for (int m = 0; m < 4; ++m) _Pragma("unroll") for (int k = 0; k < 2; ++k) dst[m][k] = *(const LAS bf16x8*)(lds + PG8_SA(b, h) + aoff + m * 2048 + k * 1024); } while (0)
; #define PG8_LDB(dst, b, h) do { _Pragma("unroll") for (int n = 0; n < 2; ++n) _Pragma("unroll") for (int k = 0; k < 2; ++k) dst[n][k] = *(const LAS bf16x8*)(lds + PG8_SB(b, h) + boff + n * 2048 + k * 1024); } while (0)
; #define PG8_MMA(ai, bj, At, Bt) do { __builtin_amdgcn_s_setprio(1); _Pragma("unroll") for (int m = 0; m < 4; ++m) _Pragma("unroll") for (int n = 0; n < 2; ++n) _Pragma("unroll") for (int k = 0; k < 2; ++k) \
;         acc[ai][bj][m][n] = __builtin_amdgcn_mfma_f32_16x16x32_bf16(Bt[n][k], At[m][k], acc[ai][bj][m][n], 0, 0, 0); __builtin_amdgcn_s_setprio(0); } while (0)
; #define PG8_WAIT_V(n) asm volatile("s_waitcnt vmcnt(" #n ")" ::: "memory")
; #define PG8_WAIT_L(n) asm volatile("s_waitcnt lgkmcnt(" #n ")" ::: "memory")
; #define PG8_BAR __builtin_amdgcn_s_barrier()
; #define PG8_SCHED __builtin_amdgcn_sched_barrier(0)
; template <int EPI> ...
;     ...
;             PG8_WAIT_V(8); PG8_WAIT_L(0); PG8_BAR; PG8_MMA(1, 0, At, B0); PG8_MMA(1, 1, At, B1); PG8_BAR; PG8_SCHED;
;             PG8_LDB(B0, 1, 0); PG8_LDB(B1, 1, 1); PG8_SCHED; PG8_LDA(At, 1, 0); PG8_STAGE(PG8_SA(0, 1), a2 + hstep);
;             PG8_WAIT_V(8); PG8_WAIT_L(0); PG8_BAR; PG8_MMA(0, 0, At, B0); PG8_MMA(0, 1, At, B1); PG8_BAR; PG8_SCHED;
	s_setprio 1
	s_waitcnt lgkmcnt(0)
	v_mfma_f32_16x16x32_bf16 v[62:65], v[142:145], v[192:195], v[62:65]
	v_mfma_f32_16x16x32_bf16 v[58:61], v[160:163], v[192:195], v[58:61]
	v_mfma_f32_16x16x32_bf16 v[54:57], v[142:145], v[200:203], v[54:57]
	v_mfma_f32_16x16x32_bf16 v[50:53], v[160:163], v[200:203], v[50:53]
	v_mfma_f32_16x16x32_bf16 v[42:45], v[142:145], v[208:211], v[42:45]
	v_mfma_f32_16x16x32_bf16 v[34:37], v[160:163], v[208:211], v[34:37]
	v_mfma_f32_16x16x32_bf16 v[26:29], v[142:145], v[216:219], v[26:29]
	v_mfma_f32_16x16x32_bf16 v[18:21], v[160:163], v[216:219], v[18:21]
	v_mfma_f32_16x16x32_bf16 v[62:65], v[156:159], v[196:199], v[62:65]
	v_mfma_f32_16x16x32_bf16 v[58:61], v[164:167], v[196:199], v[58:61]
	v_mfma_f32_16x16x32_bf16 v[54:57], v[156:159], v[204:207], v[54:57]
	v_mfma_f32_16x16x32_bf16 v[50:53], v[164:167], v[204:207], v[50:53]
	v_mfma_f32_16x16x32_bf16 v[42:45], v[156:159], v[212:215], v[42:45]
	v_mfma_f32_16x16x32_bf16 v[34:37], v[164:167], v[212:215], v[34:37]
	v_mfma_f32_16x16x32_bf16 v[26:29], v[156:159], v[220:223], v[26:29]
	v_mfma_f32_16x16x32_bf16 v[18:21], v[164:167], v[220:223], v[18:21]
	s_setprio 0
	s_setprio 1
	v_mfma_f32_16x16x32_bf16 v[46:49], v[168:171], v[192:195], v[46:49]
	v_mfma_f32_16x16x32_bf16 v[38:41], v[176:179], v[192:195], v[38:41]
	v_mfma_f32_16x16x32_bf16 v[30:33], v[168:171], v[200:203], v[30:33]
	v_mfma_f32_16x16x32_bf16 v[22:25], v[176:179], v[200:203], v[22:25]
	v_mfma_f32_16x16x32_bf16 v[14:17], v[168:171], v[208:211], v[14:17]
	v_mfma_f32_16x16x32_bf16 v[10:13], v[176:179], v[208:211], v[10:13]
	v_mfma_f32_16x16x32_bf16 v[6:9], v[168:171], v[216:219], v[6:9]
	v_mfma_f32_16x16x32_bf16 v[2:5], v[176:179], v[216:219], v[2:5]
	v_mfma_f32_16x16x32_bf16 v[46:49], v[172:175], v[196:199], v[46:49]
	v_mfma_f32_16x16x32_bf16 v[38:41], v[188:191], v[196:199], v[38:41]
	v_mfma_f32_16x16x32_bf16 v[30:33], v[172:175], v[204:207], v[30:33]
	v_mfma_f32_16x16x32_bf16 v[22:25], v[188:191], v[204:207], v[22:25]
	v_mfma_f32_16x16x32_bf16 v[14:17], v[172:175], v[212:215], v[14:17]
	v_mfma_f32_16x16x32_bf16 v[10:13], v[188:191], v[212:215], v[10:13]
	v_mfma_f32_16x16x32_bf16 v[6:9], v[172:175], v[220:223], v[6:9]
	v_mfma_f32_16x16x32_bf16 v[2:5], v[188:191], v[220:223], v[2:5]
	s_setprio 0
	s_barrier
	s_add_i32 s58, 0, 0x18000
	s_add_i32 s59, 0, 0x1c000
	s_add_u32 s36, s36, 0x40000
	s_addc_u32 s37, s37, 0
	s_mov_b32 m0, s41
	v_lshl_add_u64 v[228:229], s[36:37], 0, v[130:131]
	global_load_lds_dwordx4 v[228:229], off
	v_lshl_add_u64 v[228:229], s[36:37], 0, v[132:133]
	s_mov_b32 m0, s42
	s_nop 0
	global_load_lds_dwordx4 v[228:229], off
	v_add_u32_e32 v155, s58, v149
	ds_read_b128 v[142:145], v155
	ds_read_b128 v[156:159], v155 offset:1024
	ds_read_b128 v[160:163], v155 offset:2048
	ds_read_b128 v[164:167], v155 offset:3072
	v_add_u32_e32 v155, s59, v149
	ds_read_b128 v[168:171], v155
	ds_read_b128 v[172:175], v155 offset:1024
	ds_read_b128 v[176:179], v155 offset:2048
	ds_read_b128 v[188:191], v155 offset:3072
	ds_read_b128 v[192:195], v154 offset:32768
	ds_read_b128 v[196:199], v154 offset:33792
	ds_read_b128 v[200:203], v154 offset:34816
	ds_read_b128 v[204:207], v154 offset:35840
	ds_read_b128 v[208:211], v154 offset:36864
	ds_read_b128 v[212:215], v154 offset:37888
	ds_read_b128 v[216:219], v154 offset:38912
	ds_read_b128 v[220:223], v154 offset:39936
	s_waitcnt vmcnt(8)
	s_waitcnt lgkmcnt(0)
	s_barrier
	s_setprio 1
	s_waitcnt lgkmcnt(0)
	v_mfma_f32_16x16x32_bf16 v[126:129], v[142:145], v[192:195], v[126:129]
	v_mfma_f32_16x16x32_bf16 v[122:125], v[160:163], v[192:195], v[122:125]
	v_mfma_f32_16x16x32_bf16 v[118:121], v[142:145], v[200:203], v[118:121]
	v_mfma_f32_16x16x32_bf16 v[114:117], v[160:163], v[200:203], v[114:117]
	v_mfma_f32_16x16x32_bf16 v[106:109], v[142:145], v[208:211], v[106:109]
	v_mfma_f32_16x16x32_bf16 v[98:101], v[160:163], v[208:211], v[98:101]
	v_mfma_f32_16x16x32_bf16 v[90:93], v[142:145], v[216:219], v[90:93]
	v_mfma_f32_16x16x32_bf16 v[82:85], v[160:163], v[216:219], v[82:85]
	v_mfma_f32_16x16x32_bf16 v[126:129], v[156:159], v[196:199], v[126:129]
	v_mfma_f32_16x16x32_bf16 v[122:125], v[164:167], v[196:199], v[122:125]
	v_mfma_f32_16x16x32_bf16 v[118:121], v[156:159], v[204:207], v[118:121]
	v_mfma_f32_16x16x32_bf16 v[114:117], v[164:167], v[204:207], v[114:117]
	v_mfma_f32_16x16x32_bf16 v[106:109], v[156:159], v[212:215], v[106:109]
	v_mfma_f32_16x16x32_bf16 v[98:101], v[164:167], v[212:215], v[98:101]
	v_mfma_f32_16x16x32_bf16 v[90:93], v[156:159], v[220:223], v[90:93]
	v_mfma_f32_16x16x32_bf16 v[82:85], v[164:167], v[220:223], v[82:85]
	s_setprio 0
	s_setprio 1
	v_mfma_f32_16x16x32_bf16 v[110:113], v[168:171], v[192:195], v[110:113]
	v_mfma_f32_16x16x32_bf16 v[102:105], v[176:179], v[192:195], v[102:105]
	v_mfma_f32_16x16x32_bf16 v[94:97], v[168:171], v[200:203], v[94:97]
	v_mfma_f32_16x16x32_bf16 v[86:89], v[176:179], v[200:203], v[86:89]
	v_mfma_f32_16x16x32_bf16 v[78:81], v[168:171], v[208:211], v[78:81]
	v_mfma_f32_16x16x32_bf16 v[74:77], v[176:179], v[208:211], v[74:77]
	v_mfma_f32_16x16x32_bf16 v[70:73], v[168:171], v[216:219], v[70:73]
	v_mfma_f32_16x16x32_bf16 v[66:69], v[176:179], v[216:219], v[66:69]
	v_mfma_f32_16x16x32_bf16 v[110:113], v[172:175], v[196:199], v[110:113]
	v_mfma_f32_16x16x32_bf16 v[102:105], v[188:191], v[196:199], v[102:105]
	v_mfma_f32_16x16x32_bf16 v[94:97], v[172:175], v[204:207], v[94:97]
	v_mfma_f32_16x16x32_bf16 v[86:89], v[188:191], v[204:207], v[86:89]
	v_mfma_f32_16x16x32_bf16 v[78:81], v[172:175], v[212:215], v[78:81]
	v_mfma_f32_16x16x32_bf16 v[74:77], v[188:191], v[212:215], v[74:77]
	v_mfma_f32_16x16x32_bf16 v[70:73], v[172:175], v[220:223], v[70:73]
	v_mfma_f32_16x16x32_bf16 v[66:69], v[188:191], v[220:223], v[66:69]
	s_setprio 0
	s_barrier
; #define PG8_STAGE(bufoff, gbase) do { _Pragma("unroll") for (int _i = 0; _i < 2; ++_i) \
;         __builtin_amdgcn_global_load_lds((const unsigned*)((const char*)(gbase) + voff[_i]), (LAS unsigned*)(lds + (bufoff) + ldsw + _i * 8192), 16, 0, 0); } while (0)
; #define PG8_LDA(dst, b, h) do { _Pragma("unroll") for (int m = 0; m < 4; ++m) _Pragma("unroll") for (int k = 0; k < 2; ++k) dst[m][k] = *(const LAS bf16x8*)(lds + PG8_SA(b, h) + aoff + m * 2048 + k * 1024); } while (0)
; #define PG8_MMA(ai, bj, At, Bt) do { __builtin_amdgcn_s_setprio(1); _Pragma("unroll") for (int m = 0; m < 4; ++m) _Pragma("unroll") for (int n = 0; n < 2; ++n) _Pragma("unroll") for (int k = 0; k < 2; ++k) \
;         acc[ai][bj][m][n] = __builtin_amdgcn_mfma_f32_16x16x32_bf16(Bt[n][k], At[m][k], acc[ai][bj][m][n], 0, 0, 0); __builtin_amdgcn_s_setprio(0); } while (0)
; #define PG8_WAIT_V(n) asm volatile("s_waitcnt vmcnt(" #n ")" ::: "memory")
; #define PG8_WAIT_L(n) asm volatile("s_waitcnt lgkmcnt(" #n ")" ::: "memory")
; #define PG8_BAR __builtin_amdgcn_s_barrier()
; #define PG8_SCHED __builtin_amdgcn_sched_barrier(0)
; template <int EPI> ...
;     ...
;             PG8_LDA(At, 1, 1); PG8_STAGE(PG8_SB(1, 0), b3); PG8_STAGE(PG8_SB(1, 1), b3 + hstep); PG8_STAGE(PG8_SA(1, 0), a3);
;             PG8_WAIT_V(8); PG8_WAIT_L(0); PG8_BAR; PG8_MMA(1, 0, At, B0); PG8_MMA(1, 1, At, B1); PG8_BAR; PG8_SCHED;
;         }
;         if (wr == 0) PG8_BAR;
;         if (SPLIT && cur_slice >= 0) {
	s_add_i32 s36, s58, s39
	v_lshl_add_u64 v[146:147], v[146:147], 0, s[10:11]
	s_mov_b32 m0, s36
	s_nop 0
	global_load_lds_dwordx4 v[146:147], off
	s_add_i32 m0, s36, 0x2000
	s_add_u32 s34, s34, 0x40080
	v_lshl_add_u64 v[146:147], v[180:181], 0, s[10:11]
	s_addc_u32 s35, s35, 0
	s_add_i32 s36, s59, s39
	global_load_lds_dwordx4 v[146:147], off
	v_lshl_add_u64 v[146:147], s[34:35], 0, v[130:131]
	s_mov_b32 m0, s36
	s_nop 0
	global_load_lds_dwordx4 v[146:147], off
	v_lshl_add_u64 v[146:147], s[34:35], 0, v[132:133]
	s_add_i32 m0, s36, 0x2000
	s_nop 0
	global_load_lds_dwordx4 v[146:147], off
	v_lshl_add_u64 v[146:147], v[224:225], 0, s[10:11]
	s_mov_b32 m0, s43
	s_nop 0
	global_load_lds_dwordx4 v[146:147], off
	v_lshl_add_u64 v[146:147], v[226:227], 0, s[10:11]
	s_mov_b32 m0, s44
	s_nop 0
	global_load_lds_dwordx4 v[146:147], off
	ds_read_b128 v[192:195], v154 offset:49152
	ds_read_b128 v[196:199], v154 offset:50176
	ds_read_b128 v[200:203], v154 offset:51200
	ds_read_b128 v[204:207], v154 offset:52224
	ds_read_b128 v[208:211], v154 offset:53248
	ds_read_b128 v[212:215], v154 offset:54272
	ds_read_b128 v[216:219], v154 offset:55296
	ds_read_b128 v[220:223], v154 offset:56320
	s_waitcnt vmcnt(8)
	s_waitcnt lgkmcnt(0)
	s_barrier
	s_setprio 1
	s_waitcnt lgkmcnt(0)
	v_mfma_f32_16x16x32_bf16 v[62:65], v[142:145], v[192:195], v[62:65]
	v_mfma_f32_16x16x32_bf16 v[58:61], v[160:163], v[192:195], v[58:61]
	v_mfma_f32_16x16x32_bf16 v[54:57], v[142:145], v[200:203], v[54:57]
	v_mfma_f32_16x16x32_bf16 v[50:53], v[160:163], v[200:203], v[50:53]
	v_mfma_f32_16x16x32_bf16 v[42:45], v[142:145], v[208:211], v[42:45]
	v_mfma_f32_16x16x32_bf16 v[34:37], v[160:163], v[208:211], v[34:37]
	v_mfma_f32_16x16x32_bf16 v[26:29], v[142:145], v[216:219], v[26:29]
	v_mfma_f32_16x16x32_bf16 v[18:21], v[160:163], v[216:219], v[18:21]
	v_mfma_f32_16x16x32_bf16 v[62:65], v[156:159], v[196:199], v[62:65]
	v_mfma_f32_16x16x32_bf16 v[58:61], v[164:167], v[196:199], v[58:61]
	v_mfma_f32_16x16x32_bf16 v[54:57], v[156:159], v[204:207], v[54:57]
	v_mfma_f32_16x16x32_bf16 v[50:53], v[164:167], v[204:207], v[50:53]
	v_mfma_f32_16x16x32_bf16 v[42:45], v[156:159], v[212:215], v[42:45]
	v_mfma_f32_16x16x32_bf16 v[34:37], v[164:167], v[212:215], v[34:37]
	v_mfma_f32_16x16x32_bf16 v[26:29], v[156:159], v[220:223], v[26:29]
	v_mfma_f32_16x16x32_bf16 v[18:21], v[164:167], v[220:223], v[18:21]
	s_setprio 0
	s_setprio 1
	v_mfma_f32_16x16x32_bf16 v[46:49], v[168:171], v[192:195], v[46:49]
	v_mfma_f32_16x16x32_bf16 v[38:41], v[176:179], v[192:195], v[38:41]
	v_mfma_f32_16x16x32_bf16 v[30:33], v[168:171], v[200:203], v[30:33]
	v_mfma_f32_16x16x32_bf16 v[22:25], v[176:179], v[200:203], v[22:25]
	v_mfma_f32_16x16x32_bf16 v[14:17], v[168:171], v[208:211], v[14:17]
	v_mfma_f32_16x16x32_bf16 v[10:13], v[176:179], v[208:211], v[10:13]
	v_mfma_f32_16x16x32_bf16 v[6:9], v[168:171], v[216:219], v[6:9]
	v_mfma_f32_16x16x32_bf16 v[2:5], v[176:179], v[216:219], v[2:5]
	v_mfma_f32_16x16x32_bf16 v[46:49], v[172:175], v[196:199], v[46:49]
	v_mfma_f32_16x16x32_bf16 v[38:41], v[188:191], v[196:199], v[38:41]
	v_mfma_f32_16x16x32_bf16 v[30:33], v[172:175], v[204:207], v[30:33]
	v_mfma_f32_16x16x32_bf16 v[22:25], v[188:191], v[204:207], v[22:25]
	v_mfma_f32_16x16x32_bf16 v[14:17], v[172:175], v[212:215], v[14:17]
	v_mfma_f32_16x16x32_bf16 v[10:13], v[188:191], v[212:215], v[10:13]
	v_mfma_f32_16x16x32_bf16 v[6:9], v[172:175], v[220:223], v[6:9]
	v_mfma_f32_16x16x32_bf16 v[2:5], v[188:191], v[220:223], v[2:5]
	s_setprio 0
	s_barrier
	s_add_u32 s30, s30, 0x100
	s_addc_u32 s31, s31, 0
	s_add_u32 s55, s55, 0x100
	s_addc_u32 s56, s56, 0
	s_cmp_ge_u32 s57, s52
	s_mov_b32 s34, s57
	s_cbranch_scc0 .LBB0_825
	s_and_b64 vcc, exec, s[12:13]
	s_cbranch_vccz .LBB0_830
	s_barrier
	s_cmp_lt_i32 s0, 0
	s_mov_b64 s[30:31], -1
	s_cbranch_scc1 .LBB0_831

; #define PG8_STAGE(bufoff, gbase) do { _Pragma("unroll") for (int _i = 0; _i < 2; ++_i) \
;         __builtin_amdgcn_global_load_lds((const unsigned*)((const char*)(gbase) + voff[_i]), (LAS unsigned*)(lds + (bufoff) + ldsw + _i * 8192), 16, 0, 0); } while (0)
; #define PG8_LDA(dst, b, h) do { _Pragma("unroll") for (int m = 0; m < 4; ++m) _Pragma("unroll") for (int k = 0; k < 2; ++k) dst[m][k] = *(const LAS bf16x8*)(lds + PG8_SA(b, h) + aoff + m * 2048 + k * 1024); } while (0)
; #define PG8_LDB(dst, b, h) do { _Pragma("unroll") for (int n = 0; n < 2; ++n) _Pragma("unroll") for (int k = 0; k < 2; ++k) dst[n][k] = *(const LAS bf16x8*)(lds + PG8_SB(b, h) + boff + n * 2048 + k * 1024); } while (0)
; #define PG8_MMA(ai, bj, At, Bt) do { __builtin_amdgcn_s_setprio(1); _Pragma("unroll") for (int m = 0; m < 4; ++m) _Pragma("unroll") for (int n = 0; n < 2; ++n) _Pragma("unroll") for (int k = 0; k < 2; ++k) \
;         acc[ai][bj][m][n] = __builtin_amdgcn_mfma_f32_16x16x32_bf16(Bt[n][k], At[m][k], acc[ai][bj][m][n], 0, 0, 0); __builtin_amdgcn_s_setprio(0); } while (0)
; #define PG8_WAIT_V(n) asm volatile("s_waitcnt vmcnt(" #n ")" ::: "memory")
; #define PG8_WAIT_L(n) asm volatile("s_waitcnt lgkmcnt(" #n ")" ::: "memory")
; #define PG8_BAR __builtin_amdgcn_s_barrier()
; #define PG8_SCHED __builtin_amdgcn_sched_barrier(0)
; template <int EPI> ...
;     ...
;             PG8_WAIT_V(8); PG8_WAIT_L(0); PG8_BAR; PG8_MMA(1, 0, At, B0); PG8_MMA(1, 1, At, B1); PG8_BAR; PG8_SCHED;
;             PG8_LDB(B0, 1, 0); PG8_LDB(B1, 1, 1); PG8_SCHED; PG8_LDA(At, 1, 0); PG8_STAGE(PG8_SA(0, 1), a2 + hstep);
;             PG8_WAIT_V(8); PG8_WAIT_L(0); PG8_BAR; PG8_MMA(0, 0, At, B0); PG8_MMA(0, 1, At, B1); PG8_BAR; PG8_SCHED;
.Lup_wdone_1:
	s_waitcnt lgkmcnt(0)
	s_barrier
	s_setprio 1
	s_waitcnt lgkmcnt(0)
	v_mfma_f32_16x16x32_bf16 v[86:89], v[38:41], v[162:165], v[86:89]
	v_mfma_f32_16x16x32_bf16 v[94:97], v[46:49], v[162:165], v[94:97]
	v_mfma_f32_16x16x32_bf16 v[62:65], v[38:41], v[170:173], v[62:65]
	v_mfma_f32_16x16x32_bf16 v[78:81], v[46:49], v[170:173], v[78:81]
	v_mfma_f32_16x16x32_bf16 v[22:25], v[38:41], v[178:181], v[22:25]
	v_mfma_f32_16x16x32_bf16 v[30:33], v[46:49], v[178:181], v[30:33]
	v_mfma_f32_16x16x32_bf16 v[14:17], v[38:41], v[218:221], v[14:17]
	v_mfma_f32_16x16x32_bf16 v[10:13], v[46:49], v[218:221], v[10:13]
	v_mfma_f32_16x16x32_bf16 v[86:89], v[42:45], v[166:169], v[86:89]
	v_mfma_f32_16x16x32_bf16 v[94:97], v[50:53], v[166:169], v[94:97]
	v_mfma_f32_16x16x32_bf16 v[62:65], v[42:45], v[174:177], v[62:65]
	v_mfma_f32_16x16x32_bf16 v[78:81], v[50:53], v[174:177], v[78:81]
	v_mfma_f32_16x16x32_bf16 v[22:25], v[42:45], v[214:217], v[22:25]
	v_mfma_f32_16x16x32_bf16 v[30:33], v[50:53], v[214:217], v[30:33]
	v_mfma_f32_16x16x32_bf16 v[14:17], v[42:45], v[222:225], v[14:17]
	v_mfma_f32_16x16x32_bf16 v[10:13], v[50:53], v[222:225], v[10:13]
	s_setprio 0
	s_setprio 1
	v_mfma_f32_16x16x32_bf16 v[34:37], v[54:57], v[170:173], v[34:37]
	v_mfma_f32_16x16x32_bf16 v[18:21], v[54:57], v[178:181], v[18:21]
	v_mfma_f32_16x16x32_bf16 v[26:29], v[66:69], v[178:181], v[26:29]
	v_mfma_f32_16x16x32_bf16 v[6:9], v[54:57], v[218:221], v[6:9]
	v_mfma_f32_16x16x32_bf16 v[2:5], v[66:69], v[218:221], v[2:5]
	v_mfma_f32_16x16x32_bf16 v[38:41], v[54:57], v[162:165], v[82:85]
	v_mfma_f32_16x16x32_bf16 v[42:45], v[66:69], v[162:165], v[90:93]
	v_mfma_f32_16x16x32_bf16 v[34:37], v[58:61], v[174:177], v[34:37]
	v_mfma_f32_16x16x32_bf16 v[46:49], v[66:69], v[170:173], v[74:77]
	v_mfma_f32_16x16x32_bf16 v[18:21], v[58:61], v[214:217], v[18:21]
	v_mfma_f32_16x16x32_bf16 v[26:29], v[70:73], v[214:217], v[26:29]
	v_mfma_f32_16x16x32_bf16 v[6:9], v[58:61], v[222:225], v[6:9]
	v_mfma_f32_16x16x32_bf16 v[2:5], v[70:73], v[222:225], v[2:5]
	v_mfma_f32_16x16x32_bf16 v[38:41], v[58:61], v[166:169], v[38:41]
	v_mfma_f32_16x16x32_bf16 v[42:45], v[70:73], v[166:169], v[42:45]
	v_mfma_f32_16x16x32_bf16 v[46:49], v[70:73], v[174:177], v[46:49]
	s_setprio 0
	s_barrier
	s_add_i32 s84, 0, 0x18000
	s_add_i32 s85, 0, 0x1c000
	s_add_u32 s60, s60, 0x40000
	s_addc_u32 s61, s61, 0
	s_mov_b32 m0, s68
	v_lshl_add_u64 v[226:227], s[60:61], 0, v[194:195]
	global_load_lds_dwordx4 v[226:227], off
	v_lshl_add_u64 v[226:227], s[60:61], 0, v[196:197]
	s_mov_b32 m0, s69
	s_nop 0
	global_load_lds_dwordx4 v[226:227], off
	v_add_u32_e32 v66, s84, v183
	v_add_u32_e32 v74, s85, v183
	ds_read_b128 v[50:53], v66
	ds_read_b128 v[54:57], v66 offset:1024
	ds_read_b128 v[58:61], v66 offset:2048
	ds_read_b128 v[66:69], v66 offset:3072
	ds_read_b128 v[70:73], v74
	ds_read_b128 v[162:165], v74 offset:1024
	ds_read_b128 v[166:169], v74 offset:2048
	ds_read_b128 v[170:173], v74 offset:3072
	ds_read_b128 v[74:77], v193 offset:32768
	ds_read_b128 v[82:85], v193 offset:33792
	ds_read_b128 v[90:93], v193 offset:34816
	ds_read_b128 v[174:177], v193 offset:35840
	ds_read_b128 v[178:181], v193 offset:36864
	ds_read_b128 v[214:217], v193 offset:37888
	ds_read_b128 v[218:221], v193 offset:38912
	ds_read_b128 v[222:225], v193 offset:39936
	s_waitcnt vmcnt(8)
	s_waitcnt lgkmcnt(0)
	s_barrier
	s_setprio 1
	s_waitcnt lgkmcnt(0)
	v_mfma_f32_16x16x32_bf16 v[150:153], v[50:53], v[74:77], v[150:153]
	v_mfma_f32_16x16x32_bf16 v[158:161], v[58:61], v[74:77], v[158:161]
	v_mfma_f32_16x16x32_bf16 v[134:137], v[50:53], v[90:93], v[134:137]
	v_mfma_f32_16x16x32_bf16 v[142:145], v[58:61], v[90:93], v[142:145]
	v_mfma_f32_16x16x32_bf16 v[118:121], v[50:53], v[178:181], v[118:121]
	v_mfma_f32_16x16x32_bf16 v[126:129], v[58:61], v[178:181], v[126:129]
	v_mfma_f32_16x16x32_bf16 v[110:113], v[50:53], v[218:221], v[110:113]
	v_mfma_f32_16x16x32_bf16 v[106:109], v[58:61], v[218:221], v[106:109]
	v_mfma_f32_16x16x32_bf16 v[150:153], v[54:57], v[82:85], v[150:153]
	v_mfma_f32_16x16x32_bf16 v[158:161], v[66:69], v[82:85], v[158:161]
	v_mfma_f32_16x16x32_bf16 v[134:137], v[54:57], v[174:177], v[134:137]
	v_mfma_f32_16x16x32_bf16 v[142:145], v[66:69], v[174:177], v[142:145]
	v_mfma_f32_16x16x32_bf16 v[118:121], v[54:57], v[214:217], v[118:121]
	v_mfma_f32_16x16x32_bf16 v[126:129], v[66:69], v[214:217], v[126:129]
	v_mfma_f32_16x16x32_bf16 v[110:113], v[54:57], v[222:225], v[110:113]
	v_mfma_f32_16x16x32_bf16 v[106:109], v[66:69], v[222:225], v[106:109]
	s_setprio 0
	s_setprio 1
	v_mfma_f32_16x16x32_bf16 v[146:149], v[70:73], v[74:77], v[146:149]
	v_mfma_f32_16x16x32_bf16 v[74:77], v[166:169], v[74:77], v[154:157]
	v_mfma_f32_16x16x32_bf16 v[154:157], v[170:173], v[82:85], v[74:77]
	v_mfma_f32_16x16x32_bf16 v[74:77], v[70:73], v[90:93], v[130:133]
	v_mfma_f32_16x16x32_bf16 v[130:133], v[162:165], v[174:177], v[74:77]
	v_mfma_f32_16x16x32_bf16 v[74:77], v[166:169], v[90:93], v[138:141]
	v_mfma_f32_16x16x32_bf16 v[138:141], v[170:173], v[174:177], v[74:77]
	v_mfma_f32_16x16x32_bf16 v[74:77], v[70:73], v[178:181], v[114:117]
	v_mfma_f32_16x16x32_bf16 v[114:117], v[162:165], v[214:217], v[74:77]
	v_mfma_f32_16x16x32_bf16 v[74:77], v[166:169], v[178:181], v[122:125]
	v_mfma_f32_16x16x32_bf16 v[122:125], v[170:173], v[214:217], v[74:77]
	v_mfma_f32_16x16x32_bf16 v[74:77], v[70:73], v[218:221], v[102:105]
	v_mfma_f32_16x16x32_bf16 v[102:105], v[162:165], v[222:225], v[74:77]
	v_mfma_f32_16x16x32_bf16 v[74:77], v[166:169], v[218:221], v[98:101]
	v_mfma_f32_16x16x32_bf16 v[146:149], v[162:165], v[82:85], v[146:149]
	v_mfma_f32_16x16x32_bf16 v[98:101], v[170:173], v[222:225], v[74:77]
	s_setprio 0
	s_barrier
; #define PG8_STAGE(bufoff, gbase) do { _Pragma("unroll") for (int _i = 0; _i < 2; ++_i) \
;         __builtin_amdgcn_global_load_lds((const unsigned*)((const char*)(gbase) + voff[_i]), (LAS unsigned*)(lds + (bufoff) + ldsw + _i * 8192), 16, 0, 0); } while (0)
; #define PG8_LDA(dst, b, h) do { _Pragma("unroll") for (int m = 0; m < 4; ++m) _Pragma("unroll") for (int k = 0; k < 2; ++k) dst[m][k] = *(const LAS bf16x8*)(lds + PG8_SA(b, h) + aoff + m * 2048 + k * 1024); } while (0)
; #define PG8_MMA(ai, bj, At, Bt) do { __builtin_amdgcn_s_setprio(1); _Pragma("unroll") for (int m = 0; m < 4; ++m) _Pragma("unroll") for (int n = 0; n < 2; ++n) _Pragma("unroll") for (int k = 0; k < 2; ++k) \
;         acc[ai][bj][m][n] = __builtin_amdgcn_mfma_f32_16x16x32_bf16(Bt[n][k], At[m][k], acc[ai][bj][m][n], 0, 0, 0); __builtin_amdgcn_s_setprio(0); } while (0)
; #define PG8_WAIT_V(n) asm volatile("s_waitcnt vmcnt(" #n ")" ::: "memory")
; #define PG8_WAIT_L(n) asm volatile("s_waitcnt lgkmcnt(" #n ")" ::: "memory")
; #define PG8_BAR __builtin_amdgcn_s_barrier()
; #define PG8_SCHED __builtin_amdgcn_sched_barrier(0)
; template <int EPI> ...
;     ...
;             PG8_LDA(At, 1, 1); PG8_STAGE(PG8_SB(1, 0), b3); PG8_STAGE(PG8_SB(1, 1), b3 + hstep); PG8_STAGE(PG8_SA(1, 0), a3);
;             PG8_WAIT_V(8); PG8_WAIT_L(0); PG8_BAR; PG8_MMA(1, 0, At, B0); PG8_MMA(1, 1, At, B1); PG8_BAR; PG8_SCHED;
;         }
;         if (wr == 0) PG8_BAR;
	s_add_i32 s60, s84, s65
	v_lshl_add_u64 v[82:83], v[230:231], 0, s[26:27]
	s_mov_b32 m0, s60
	s_nop 0
	global_load_lds_dwordx4 v[82:83], off
	s_add_i32 m0, s60, 0x2000
	s_add_u32 s58, s58, 0x40080
	v_lshl_add_u64 v[82:83], v[232:233], 0, s[26:27]
	s_addc_u32 s59, s59, 0
	s_add_i32 s60, s85, s65
	global_load_lds_dwordx4 v[82:83], off
	v_lshl_add_u64 v[82:83], s[58:59], 0, v[194:195]
	s_mov_b32 m0, s60
	s_nop 0
	global_load_lds_dwordx4 v[82:83], off
	v_lshl_add_u64 v[82:83], s[58:59], 0, v[196:197]
	s_add_i32 m0, s60, 0x2000
	s_nop 0
	global_load_lds_dwordx4 v[82:83], off
	v_lshl_add_u64 v[82:83], v[234:235], 0, s[26:27]
	s_mov_b32 m0, s72
	s_nop 0
	global_load_lds_dwordx4 v[82:83], off
	v_lshl_add_u64 v[82:83], v[236:237], 0, s[26:27]
	s_mov_b32 m0, s73
	s_nop 0
	global_load_lds_dwordx4 v[82:83], off
	ds_read_b128 v[74:77], v193 offset:49152
	ds_read_b128 v[90:93], v193 offset:50176
	ds_read_b128 v[174:177], v193 offset:51200
	ds_read_b128 v[178:181], v193 offset:52224
	ds_read_b128 v[214:217], v193 offset:53248
	ds_read_b128 v[218:221], v193 offset:54272
	ds_read_b128 v[222:225], v193 offset:55296
	ds_read_b128 v[226:229], v193 offset:56320
	s_waitcnt vmcnt(8)
	s_waitcnt lgkmcnt(0)
	s_barrier
	s_setprio 1
	s_waitcnt lgkmcnt(0)
	v_mfma_f32_16x16x32_bf16 v[82:85], v[50:53], v[74:77], v[86:89]
	v_mfma_f32_16x16x32_bf16 v[86:89], v[54:57], v[90:93], v[82:85]
	v_mfma_f32_16x16x32_bf16 v[82:85], v[58:61], v[74:77], v[94:97]
	v_mfma_f32_16x16x32_bf16 v[62:65], v[50:53], v[174:177], v[62:65]
	v_mfma_f32_16x16x32_bf16 v[78:81], v[58:61], v[174:177], v[78:81]
	v_mfma_f32_16x16x32_bf16 v[22:25], v[50:53], v[214:217], v[22:25]
	v_mfma_f32_16x16x32_bf16 v[30:33], v[58:61], v[214:217], v[30:33]
	v_mfma_f32_16x16x32_bf16 v[14:17], v[50:53], v[222:225], v[14:17]
	v_mfma_f32_16x16x32_bf16 v[10:13], v[58:61], v[222:225], v[10:13]
	v_mfma_f32_16x16x32_bf16 v[94:97], v[66:69], v[90:93], v[82:85]
	v_mfma_f32_16x16x32_bf16 v[62:65], v[54:57], v[178:181], v[62:65]
	v_mfma_f32_16x16x32_bf16 v[78:81], v[66:69], v[178:181], v[78:81]
	v_mfma_f32_16x16x32_bf16 v[22:25], v[54:57], v[218:221], v[22:25]
	v_mfma_f32_16x16x32_bf16 v[30:33], v[66:69], v[218:221], v[30:33]
	v_mfma_f32_16x16x32_bf16 v[14:17], v[54:57], v[226:229], v[14:17]
	v_mfma_f32_16x16x32_bf16 v[10:13], v[66:69], v[226:229], v[10:13]
	s_setprio 0
	s_setprio 1
	v_mfma_f32_16x16x32_bf16 v[38:41], v[70:73], v[74:77], v[38:41]
	v_mfma_f32_16x16x32_bf16 v[82:85], v[162:165], v[90:93], v[38:41]
	v_mfma_f32_16x16x32_bf16 v[38:41], v[166:169], v[74:77], v[42:45]
	v_mfma_f32_16x16x32_bf16 v[90:93], v[170:173], v[90:93], v[38:41]
	v_mfma_f32_16x16x32_bf16 v[34:37], v[70:73], v[174:177], v[34:37]
	v_mfma_f32_16x16x32_bf16 v[38:41], v[166:169], v[174:177], v[46:49]
	v_mfma_f32_16x16x32_bf16 v[18:21], v[70:73], v[214:217], v[18:21]
	v_mfma_f32_16x16x32_bf16 v[26:29], v[166:169], v[214:217], v[26:29]
	v_mfma_f32_16x16x32_bf16 v[6:9], v[70:73], v[222:225], v[6:9]
	v_mfma_f32_16x16x32_bf16 v[2:5], v[166:169], v[222:225], v[2:5]
	v_mfma_f32_16x16x32_bf16 v[34:37], v[162:165], v[178:181], v[34:37]
	v_mfma_f32_16x16x32_bf16 v[74:77], v[170:173], v[178:181], v[38:41]
	v_mfma_f32_16x16x32_bf16 v[18:21], v[162:165], v[218:221], v[18:21]
	v_mfma_f32_16x16x32_bf16 v[26:29], v[170:173], v[218:221], v[26:29]
	v_mfma_f32_16x16x32_bf16 v[6:9], v[162:165], v[226:229], v[6:9]
	v_mfma_f32_16x16x32_bf16 v[2:5], v[170:173], v[226:229], v[2:5]
	s_setprio 0
	s_barrier
	s_add_i32 s83, s83, 2
	s_add_u32 s56, s56, 0x100
	s_addc_u32 s57, s57, 0
	s_add_u32 s62, s62, 0x100
	s_addc_u32 s63, s63, 0
	s_cmp_gt_u32 s83, 13
	s_cbranch_scc0 .LBB0_970
	s_and_b64 vcc, exec, s[28:29]
	s_cbranch_vccz .LBB0_973
	s_barrier

; #define PG8_STAGE(bufoff, gbase) do { _Pragma("unroll") for (int _i = 0; _i < 2; ++_i) \
;         __builtin_amdgcn_global_load_lds((const unsigned*)((const char*)(gbase) + voff[_i]), (LAS unsigned*)(lds + (bufoff) + ldsw + _i * 8192), 16, 0, 0); } while (0)
; #define PG8_LDA(dst, b, h) do { _Pragma("unroll") for (int m = 0; m < 4; ++m) _Pragma("unroll") for (int k = 0; k < 2; ++k) dst[m][k] = *(const LAS bf16x8*)(lds + PG8_SA(b, h) + aoff + m * 2048 + k * 1024); } while (0)
; #define PG8_LDB(dst, b, h) do { _Pragma("unroll") for (int n = 0; n < 2; ++n) _Pragma("unroll") for (int k = 0; k < 2; ++k) dst[n][k] = *(const LAS bf16x8*)(lds + PG8_SB(b, h) + boff + n * 2048 + k * 1024); } while (0)
; #define PG8_MMA(ai, bj, At, Bt) do { __builtin_amdgcn_s_setprio(1); _Pragma("unroll") for (int m = 0; m < 4; ++m) _Pragma("unroll") for (int n = 0; n < 2; ++n) _Pragma("unroll") for (int k = 0; k < 2; ++k) \
;         acc[ai][bj][m][n] = __builtin_amdgcn_mfma_f32_16x16x32_bf16(Bt[n][k], At[m][k], acc[ai][bj][m][n], 0, 0, 0); __builtin_amdgcn_s_setprio(0); } while (0)
; #define PG8_WAIT_V(n) asm volatile("s_waitcnt vmcnt(" #n ")" ::: "memory")
; #define PG8_WAIT_L(n) asm volatile("s_waitcnt lgkmcnt(" #n ")" ::: "memory")
; #define PG8_BAR __builtin_amdgcn_s_barrier()
; #define PG8_SCHED __builtin_amdgcn_sched_barrier(0)
; template <int EPI> ...
;     ...
;             PG8_LDB(B0, 0, 0); PG8_LDB(B1, 0, 1); PG8_SCHED; PG8_LDA(At, 0, 0); PG8_STAGE(PG8_SA(1, 1), a1 + hstep);
;             PG8_WAIT_V(8); PG8_WAIT_L(0); PG8_BAR; PG8_MMA(0, 0, At, B0); PG8_MMA(0, 1, At, B1); PG8_BAR; PG8_SCHED;
;             PG8_LDA(At, 0, 1); PG8_STAGE(PG8_SB(0, 0), b2); PG8_STAGE(PG8_SB(0, 1), b2 + hstep); PG8_STAGE(PG8_SA(0, 0), a2);
;             PG8_WAIT_V(8); PG8_WAIT_L(0); PG8_BAR; PG8_MMA(1, 0, At, B0); PG8_MMA(1, 1, At, B1); PG8_BAR; PG8_SCHED;
.LBB0_1246:
	s_add_i32 s57, s28, 2
	s_add_u32 s26, s24, 0x100
	s_addc_u32 s27, s25, 0
	s_cmp_eq_u32 s54, s28
	s_cselect_b32 s28, s18, s55
	s_cselect_b32 s31, s17, s27
	s_cselect_b32 s30, s16, s26
	s_cselect_b32 s29, s19, s56
	v_lshl_add_u64 v[180:181], s[24:25], 0, v[142:143]
	s_add_i32 m0, s38, 0xc000
	s_nop 0
	global_load_lds_dwordx4 v[180:181], off
	v_lshl_add_u64 v[180:181], s[24:25], 0, v[144:145]
	s_add_i32 m0, s38, 0xe000
	s_nop 0
	global_load_lds_dwordx4 v[180:181], off
	ds_read_b128 v[128:131], v156
	ds_read_b128 v[132:135], v156 offset:1024
	ds_read_b128 v[148:151], v156 offset:2048
	ds_read_b128 v[160:163], v156 offset:3072
	ds_read_b128 v[164:167], v157
	ds_read_b128 v[168:171], v157 offset:1024
	ds_read_b128 v[172:175], v157 offset:2048
	ds_read_b128 v[176:179], v157 offset:3072
	ds_read_b128 v[194:197], v158
	ds_read_b128 v[198:201], v158 offset:1024
	ds_read_b128 v[202:205], v158 offset:2048
	ds_read_b128 v[206:209], v158 offset:3072
	ds_read_b128 v[210:213], v158 offset:4096
	ds_read_b128 v[214:217], v158 offset:5120
	ds_read_b128 v[218:221], v158 offset:6144
	ds_read_b128 v[222:225], v158 offset:7168
	s_waitcnt vmcnt(8)
	s_waitcnt lgkmcnt(0)
	s_barrier
	s_setprio 1
	s_waitcnt lgkmcnt(0)
	v_mfma_f32_16x16x32_bf16 v[124:127], v[128:131], v[194:197], v[124:127]
	v_mfma_f32_16x16x32_bf16 v[120:123], v[148:151], v[194:197], v[120:123]
	v_mfma_f32_16x16x32_bf16 v[116:119], v[128:131], v[202:205], v[116:119]
	v_mfma_f32_16x16x32_bf16 v[112:115], v[148:151], v[202:205], v[112:115]
	v_mfma_f32_16x16x32_bf16 v[104:107], v[128:131], v[210:213], v[104:107]
	v_mfma_f32_16x16x32_bf16 v[96:99], v[148:151], v[210:213], v[96:99]
	v_mfma_f32_16x16x32_bf16 v[88:91], v[128:131], v[218:221], v[88:91]
	v_mfma_f32_16x16x32_bf16 v[80:83], v[148:151], v[218:221], v[80:83]
	v_mfma_f32_16x16x32_bf16 v[124:127], v[132:135], v[198:201], v[124:127]
	v_mfma_f32_16x16x32_bf16 v[120:123], v[160:163], v[198:201], v[120:123]
	v_mfma_f32_16x16x32_bf16 v[116:119], v[132:135], v[206:209], v[116:119]
	v_mfma_f32_16x16x32_bf16 v[112:115], v[160:163], v[206:209], v[112:115]
	v_mfma_f32_16x16x32_bf16 v[104:107], v[132:135], v[214:217], v[104:107]
	v_mfma_f32_16x16x32_bf16 v[96:99], v[160:163], v[214:217], v[96:99]
	v_mfma_f32_16x16x32_bf16 v[88:91], v[132:135], v[222:225], v[88:91]
	v_mfma_f32_16x16x32_bf16 v[80:83], v[160:163], v[222:225], v[80:83]
	s_setprio 0
	s_setprio 1
	v_mfma_f32_16x16x32_bf16 v[108:111], v[164:167], v[194:197], v[108:111]
	v_mfma_f32_16x16x32_bf16 v[100:103], v[172:175], v[194:197], v[100:103]
	v_mfma_f32_16x16x32_bf16 v[92:95], v[164:167], v[202:205], v[92:95]
	v_mfma_f32_16x16x32_bf16 v[84:87], v[172:175], v[202:205], v[84:87]
	v_mfma_f32_16x16x32_bf16 v[76:79], v[164:167], v[210:213], v[76:79]
	v_mfma_f32_16x16x32_bf16 v[72:75], v[172:175], v[210:213], v[72:75]
	v_mfma_f32_16x16x32_bf16 v[68:71], v[164:167], v[218:221], v[68:71]
	v_mfma_f32_16x16x32_bf16 v[64:67], v[172:175], v[218:221], v[64:67]
	v_mfma_f32_16x16x32_bf16 v[108:111], v[168:171], v[198:201], v[108:111]
	v_mfma_f32_16x16x32_bf16 v[100:103], v[176:179], v[198:201], v[100:103]
	v_mfma_f32_16x16x32_bf16 v[92:95], v[168:171], v[206:209], v[92:95]
	v_mfma_f32_16x16x32_bf16 v[84:87], v[176:179], v[206:209], v[84:87]
	v_mfma_f32_16x16x32_bf16 v[76:79], v[168:171], v[214:217], v[76:79]
	v_mfma_f32_16x16x32_bf16 v[72:75], v[176:179], v[214:217], v[72:75]
	v_mfma_f32_16x16x32_bf16 v[68:71], v[168:171], v[222:225], v[68:71]
	v_mfma_f32_16x16x32_bf16 v[64:67], v[176:179], v[222:225], v[64:67]
	s_setprio 0
	s_barrier
	s_add_i32 s24, s45, s37
	v_lshl_add_u64 v[180:181], s[28:29], 0, v[136:137]
	s_mov_b32 m0, s24
	s_nop 0
	global_load_lds_dwordx4 v[180:181], off
	s_add_i32 m0, s24, 0x2000
	s_add_u32 s24, s28, 0xb0000
	v_lshl_add_u64 v[186:187], s[28:29], 0, v[138:139]
	s_addc_u32 s25, s29, 0
	s_add_i32 s58, s46, s37
	global_load_lds_dwordx4 v[186:187], off
	v_lshl_add_u64 v[226:227], s[24:25], 0, v[136:137]
	s_mov_b32 m0, s58
	v_lshl_add_u64 v[228:229], s[30:31], 0, v[138:139]
	global_load_lds_dwordx4 v[226:227], off
	v_lshl_add_u64 v[226:227], s[24:25], 0, v[138:139]
	s_add_i32 m0, s58, 0x2000
	s_nop 0
	global_load_lds_dwordx4 v[226:227], off
	v_lshl_add_u64 v[226:227], s[30:31], 0, v[136:137]
	s_mov_b32 m0, s38
	s_nop 0
	global_load_lds_dwordx4 v[226:227], off
	s_mov_b32 m0, s39
	s_nop 0
	global_load_lds_dwordx4 v[228:229], off
	ds_read_b128 v[194:197], v158 offset:16384
	ds_read_b128 v[198:201], v158 offset:17408
	ds_read_b128 v[202:205], v158 offset:18432
	ds_read_b128 v[206:209], v158 offset:19456
	ds_read_b128 v[210:213], v158 offset:20480
	ds_read_b128 v[214:217], v158 offset:21504
	ds_read_b128 v[218:221], v158 offset:22528
	ds_read_b128 v[222:225], v158 offset:23552
	s_waitcnt vmcnt(8)
	s_waitcnt lgkmcnt(0)
	s_barrier
; #define PG8_STAGE(bufoff, gbase) do { _Pragma("unroll") for (int _i = 0; _i < 2; ++_i) \
;         __builtin_amdgcn_global_load_lds((const unsigned*)((const char*)(gbase) + voff[_i]), (LAS unsigned*)(lds + (bufoff) + ldsw + _i * 8192), 16, 0, 0); } while (0)
; #define PG8_LDA(dst, b, h) do { _Pragma("unroll") for (int m = 0; m < 4; ++m) _Pragma("unroll") for (int k = 0; k < 2; ++k) dst[m][k] = *(const LAS bf16x8*)(lds + PG8_SA(b, h) + aoff + m * 2048 + k * 1024); } while (0)
; #define PG8_LDB(dst, b, h) do { _Pragma("unroll") for (int n = 0; n < 2; ++n) _Pragma("unroll") for (int k = 0; k < 2; ++k) dst[n][k] = *(const LAS bf16x8*)(lds + PG8_SB(b, h) + boff + n * 2048 + k * 1024); } while (0)
; #define PG8_MMA(ai, bj, At, Bt) do { __builtin_amdgcn_s_setprio(1); _Pragma("unroll") for (int m = 0; m < 4; ++m) _Pragma("unroll") for (int n = 0; n < 2; ++n) _Pragma("unroll") for (int k = 0; k < 2; ++k) \
;         acc[ai][bj][m][n] = __builtin_amdgcn_mfma_f32_16x16x32_bf16(Bt[n][k], At[m][k], acc[ai][bj][m][n], 0, 0, 0); __builtin_amdgcn_s_setprio(0); } while (0)
; #define PG8_WAIT_V(n) asm volatile("s_waitcnt vmcnt(" #n ")" ::: "memory")
; #define PG8_WAIT_L(n) asm volatile("s_waitcnt lgkmcnt(" #n ")" ::: "memory")
; #define PG8_BAR __builtin_amdgcn_s_barrier()
; #define PG8_SCHED __builtin_amdgcn_sched_barrier(0)
; template <int EPI> ...
;     ...
;             PG8_WAIT_V(8); PG8_WAIT_L(0); PG8_BAR; PG8_MMA(1, 0, At, B0); PG8_MMA(1, 1, At, B1); PG8_BAR; PG8_SCHED;
;             PG8_LDB(B0, 1, 0); PG8_LDB(B1, 1, 1); PG8_SCHED; PG8_LDA(At, 1, 0); PG8_STAGE(PG8_SA(0, 1), a2 + hstep);
;             PG8_WAIT_V(8); PG8_WAIT_L(0); PG8_BAR; PG8_MMA(0, 0, At, B0); PG8_MMA(0, 1, At, B1); PG8_BAR; PG8_SCHED;
	s_setprio 1
	s_waitcnt lgkmcnt(0)
	v_mfma_f32_16x16x32_bf16 v[60:63], v[128:131], v[194:197], v[60:63]
	v_mfma_f32_16x16x32_bf16 v[56:59], v[148:151], v[194:197], v[56:59]
	v_mfma_f32_16x16x32_bf16 v[52:55], v[128:131], v[202:205], v[52:55]
	v_mfma_f32_16x16x32_bf16 v[48:51], v[148:151], v[202:205], v[48:51]
	v_mfma_f32_16x16x32_bf16 v[40:43], v[128:131], v[210:213], v[40:43]
	v_mfma_f32_16x16x32_bf16 v[32:35], v[148:151], v[210:213], v[32:35]
	v_mfma_f32_16x16x32_bf16 v[24:27], v[128:131], v[218:221], v[24:27]
	v_mfma_f32_16x16x32_bf16 v[16:19], v[148:151], v[218:221], v[16:19]
	v_mfma_f32_16x16x32_bf16 v[60:63], v[132:135], v[198:201], v[60:63]
	v_mfma_f32_16x16x32_bf16 v[56:59], v[160:163], v[198:201], v[56:59]
	v_mfma_f32_16x16x32_bf16 v[52:55], v[132:135], v[206:209], v[52:55]
	v_mfma_f32_16x16x32_bf16 v[48:51], v[160:163], v[206:209], v[48:51]
	v_mfma_f32_16x16x32_bf16 v[40:43], v[132:135], v[214:217], v[40:43]
	v_mfma_f32_16x16x32_bf16 v[32:35], v[160:163], v[214:217], v[32:35]
	v_mfma_f32_16x16x32_bf16 v[24:27], v[132:135], v[222:225], v[24:27]
	v_mfma_f32_16x16x32_bf16 v[16:19], v[160:163], v[222:225], v[16:19]
	s_setprio 0
	s_setprio 1
	v_mfma_f32_16x16x32_bf16 v[44:47], v[164:167], v[194:197], v[44:47]
	v_mfma_f32_16x16x32_bf16 v[36:39], v[172:175], v[194:197], v[36:39]
	v_mfma_f32_16x16x32_bf16 v[28:31], v[164:167], v[202:205], v[28:31]
	v_mfma_f32_16x16x32_bf16 v[20:23], v[172:175], v[202:205], v[20:23]
	v_mfma_f32_16x16x32_bf16 v[12:15], v[164:167], v[210:213], v[12:15]
	v_mfma_f32_16x16x32_bf16 v[8:11], v[172:175], v[210:213], v[8:11]
	v_mfma_f32_16x16x32_bf16 v[4:7], v[164:167], v[218:221], v[4:7]
	v_mfma_f32_16x16x32_bf16 v[0:3], v[172:175], v[218:221], v[0:3]
	v_mfma_f32_16x16x32_bf16 v[44:47], v[168:171], v[198:201], v[44:47]
	v_mfma_f32_16x16x32_bf16 v[36:39], v[176:179], v[198:201], v[36:39]
	v_mfma_f32_16x16x32_bf16 v[28:31], v[168:171], v[206:209], v[28:31]
	v_mfma_f32_16x16x32_bf16 v[20:23], v[176:179], v[206:209], v[20:23]
	v_mfma_f32_16x16x32_bf16 v[12:15], v[168:171], v[214:217], v[12:15]
	v_mfma_f32_16x16x32_bf16 v[8:11], v[176:179], v[214:217], v[8:11]
	v_mfma_f32_16x16x32_bf16 v[4:7], v[168:171], v[222:225], v[4:7]
	v_mfma_f32_16x16x32_bf16 v[0:3], v[176:179], v[222:225], v[0:3]
	s_setprio 0
	s_barrier
	s_add_i32 s58, 0, 0x18000
	s_add_i32 s59, 0, 0x1c000
	s_add_u32 s24, s30, 0xb0000
	s_addc_u32 s25, s31, 0
	s_mov_b32 m0, s40
	v_lshl_add_u64 v[230:231], s[24:25], 0, v[136:137]
	global_load_lds_dwordx4 v[230:231], off
	v_lshl_add_u64 v[230:231], s[24:25], 0, v[138:139]
	s_mov_b32 m0, s41
	s_nop 0
	global_load_lds_dwordx4 v[230:231], off
	v_add_u32_e32 v159, s58, v153
	ds_read_b128 v[128:131], v159
	ds_read_b128 v[132:135], v159 offset:1024
	ds_read_b128 v[148:151], v159 offset:2048
	ds_read_b128 v[160:163], v159 offset:3072
	v_add_u32_e32 v159, s59, v153
	ds_read_b128 v[164:167], v159
	ds_read_b128 v[168:171], v159 offset:1024
	ds_read_b128 v[172:175], v159 offset:2048
	ds_read_b128 v[176:179], v159 offset:3072
	ds_read_b128 v[194:197], v158 offset:32768
	ds_read_b128 v[198:201], v158 offset:33792
	ds_read_b128 v[202:205], v158 offset:34816
	ds_read_b128 v[206:209], v158 offset:35840
	ds_read_b128 v[210:213], v158 offset:36864
	ds_read_b128 v[214:217], v158 offset:37888
	ds_read_b128 v[218:221], v158 offset:38912
	ds_read_b128 v[222:225], v158 offset:39936
	s_waitcnt vmcnt(8)
	s_waitcnt lgkmcnt(0)
	s_barrier
	s_setprio 1
	s_waitcnt lgkmcnt(0)
	v_mfma_f32_16x16x32_bf16 v[124:127], v[128:131], v[194:197], v[124:127]
	v_mfma_f32_16x16x32_bf16 v[120:123], v[148:151], v[194:197], v[120:123]
	v_mfma_f32_16x16x32_bf16 v[116:119], v[128:131], v[202:205], v[116:119]
	v_mfma_f32_16x16x32_bf16 v[112:115], v[148:151], v[202:205], v[112:115]
	v_mfma_f32_16x16x32_bf16 v[104:107], v[128:131], v[210:213], v[104:107]
	v_mfma_f32_16x16x32_bf16 v[96:99], v[148:151], v[210:213], v[96:99]
	v_mfma_f32_16x16x32_bf16 v[88:91], v[128:131], v[218:221], v[88:91]
	v_mfma_f32_16x16x32_bf16 v[80:83], v[148:151], v[218:221], v[80:83]
	v_mfma_f32_16x16x32_bf16 v[124:127], v[132:135], v[198:201], v[124:127]
	v_mfma_f32_16x16x32_bf16 v[120:123], v[160:163], v[198:201], v[120:123]
	v_mfma_f32_16x16x32_bf16 v[116:119], v[132:135], v[206:209], v[116:119]
	v_mfma_f32_16x16x32_bf16 v[112:115], v[160:163], v[206:209], v[112:115]
	v_mfma_f32_16x16x32_bf16 v[104:107], v[132:135], v[214:217], v[104:107]
	v_mfma_f32_16x16x32_bf16 v[96:99], v[160:163], v[214:217], v[96:99]
	v_mfma_f32_16x16x32_bf16 v[88:91], v[132:135], v[222:225], v[88:91]
	v_mfma_f32_16x16x32_bf16 v[80:83], v[160:163], v[222:225], v[80:83]
	s_setprio 0
	s_setprio 1
	v_mfma_f32_16x16x32_bf16 v[108:111], v[164:167], v[194:197], v[108:111]
	v_mfma_f32_16x16x32_bf16 v[100:103], v[172:175], v[194:197], v[100:103]
	v_mfma_f32_16x16x32_bf16 v[92:95], v[164:167], v[202:205], v[92:95]
	v_mfma_f32_16x16x32_bf16 v[84:87], v[172:175], v[202:205], v[84:87]
	v_mfma_f32_16x16x32_bf16 v[76:79], v[164:167], v[210:213], v[76:79]
	v_mfma_f32_16x16x32_bf16 v[72:75], v[172:175], v[210:213], v[72:75]
	v_mfma_f32_16x16x32_bf16 v[68:71], v[164:167], v[218:221], v[68:71]
	v_mfma_f32_16x16x32_bf16 v[64:67], v[172:175], v[218:221], v[64:67]
	v_mfma_f32_16x16x32_bf16 v[108:111], v[168:171], v[198:201], v[108:111]
	v_mfma_f32_16x16x32_bf16 v[100:103], v[176:179], v[198:201], v[100:103]
	v_mfma_f32_16x16x32_bf16 v[92:95], v[168:171], v[206:209], v[92:95]
	v_mfma_f32_16x16x32_bf16 v[84:87], v[176:179], v[206:209], v[84:87]
	v_mfma_f32_16x16x32_bf16 v[76:79], v[168:171], v[214:217], v[76:79]
	v_mfma_f32_16x16x32_bf16 v[72:75], v[176:179], v[214:217], v[72:75]
	v_mfma_f32_16x16x32_bf16 v[68:71], v[168:171], v[222:225], v[68:71]
	v_mfma_f32_16x16x32_bf16 v[64:67], v[176:179], v[222:225], v[64:67]
	s_setprio 0
	s_barrier
; #define PG8_STAGE(bufoff, gbase) do { _Pragma("unroll") for (int _i = 0; _i < 2; ++_i) \
;         __builtin_amdgcn_global_load_lds((const unsigned*)((const char*)(gbase) + voff[_i]), (LAS unsigned*)(lds + (bufoff) + ldsw + _i * 8192), 16, 0, 0); } while (0)
; #define PG8_LDA(dst, b, h) do { _Pragma("unroll") for (int m = 0; m < 4; ++m) _Pragma("unroll") for (int k = 0; k < 2; ++k) dst[m][k] = *(const LAS bf16x8*)(lds + PG8_SA(b, h) + aoff + m * 2048 + k * 1024); } while (0)
; #define PG8_MMA(ai, bj, At, Bt) do { __builtin_amdgcn_s_setprio(1); _Pragma("unroll") for (int m = 0; m < 4; ++m) _Pragma("unroll") for (int n = 0; n < 2; ++n) _Pragma("unroll") for (int k = 0; k < 2; ++k) \
;         acc[ai][bj][m][n] = __builtin_amdgcn_mfma_f32_16x16x32_bf16(Bt[n][k], At[m][k], acc[ai][bj][m][n], 0, 0, 0); __builtin_amdgcn_s_setprio(0); } while (0)
; #define PG8_WAIT_V(n) asm volatile("s_waitcnt vmcnt(" #n ")" ::: "memory")
; #define PG8_WAIT_L(n) asm volatile("s_waitcnt lgkmcnt(" #n ")" ::: "memory")
; #define PG8_BAR __builtin_amdgcn_s_barrier()
; #define PG8_SCHED __builtin_amdgcn_sched_barrier(0)
; template <int EPI> ...
;     ...
;             PG8_LDA(At, 1, 1); PG8_STAGE(PG8_SB(1, 0), b3); PG8_STAGE(PG8_SB(1, 1), b3 + hstep); PG8_STAGE(PG8_SA(1, 0), a3);
;             PG8_WAIT_V(8); PG8_WAIT_L(0); PG8_BAR; PG8_MMA(1, 0, At, B0); PG8_MMA(1, 1, At, B1); PG8_BAR; PG8_SCHED;
;         }
;         if (wr == 0) PG8_BAR;
;         if (SPLIT && cur_slice >= 0) {
	s_add_i32 s24, s58, s37
	v_lshl_add_u64 v[180:181], v[180:181], 0, s[10:11]
	s_mov_b32 m0, s24
	s_nop 0
	global_load_lds_dwordx4 v[180:181], off
	s_add_i32 m0, s24, 0x2000
	s_add_u32 s24, s28, 0xb0080
	v_lshl_add_u64 v[180:181], v[186:187], 0, s[10:11]
	s_addc_u32 s25, s29, 0
	s_add_i32 s28, s59, s37
	global_load_lds_dwordx4 v[180:181], off
	v_lshl_add_u64 v[180:181], s[24:25], 0, v[136:137]
	s_mov_b32 m0, s28
	s_nop 0
	global_load_lds_dwordx4 v[180:181], off
	v_lshl_add_u64 v[180:181], s[24:25], 0, v[138:139]
	s_add_i32 m0, s28, 0x2000
	s_nop 0
	global_load_lds_dwordx4 v[180:181], off
	v_lshl_add_u64 v[180:181], v[226:227], 0, s[10:11]
	s_mov_b32 m0, s42
	s_nop 0
	global_load_lds_dwordx4 v[180:181], off
	v_lshl_add_u64 v[180:181], v[228:229], 0, s[10:11]
	s_mov_b32 m0, s43
	s_nop 0
	global_load_lds_dwordx4 v[180:181], off
	ds_read_b128 v[194:197], v158 offset:49152
	ds_read_b128 v[198:201], v158 offset:50176
	ds_read_b128 v[202:205], v158 offset:51200
	ds_read_b128 v[206:209], v158 offset:52224
	ds_read_b128 v[210:213], v158 offset:53248
	ds_read_b128 v[214:217], v158 offset:54272
	ds_read_b128 v[218:221], v158 offset:55296
	ds_read_b128 v[222:225], v158 offset:56320
	s_waitcnt vmcnt(8)
	s_waitcnt lgkmcnt(0)
	s_barrier
	s_setprio 1
	s_waitcnt lgkmcnt(0)
	v_mfma_f32_16x16x32_bf16 v[60:63], v[128:131], v[194:197], v[60:63]
	v_mfma_f32_16x16x32_bf16 v[56:59], v[148:151], v[194:197], v[56:59]
	v_mfma_f32_16x16x32_bf16 v[52:55], v[128:131], v[202:205], v[52:55]
	v_mfma_f32_16x16x32_bf16 v[48:51], v[148:151], v[202:205], v[48:51]
	v_mfma_f32_16x16x32_bf16 v[40:43], v[128:131], v[210:213], v[40:43]
	v_mfma_f32_16x16x32_bf16 v[32:35], v[148:151], v[210:213], v[32:35]
	v_mfma_f32_16x16x32_bf16 v[24:27], v[128:131], v[218:221], v[24:27]
	v_mfma_f32_16x16x32_bf16 v[16:19], v[148:151], v[218:221], v[16:19]
	v_mfma_f32_16x16x32_bf16 v[60:63], v[132:135], v[198:201], v[60:63]
	v_mfma_f32_16x16x32_bf16 v[56:59], v[160:163], v[198:201], v[56:59]
	v_mfma_f32_16x16x32_bf16 v[52:55], v[132:135], v[206:209], v[52:55]
	v_mfma_f32_16x16x32_bf16 v[48:51], v[160:163], v[206:209], v[48:51]
	v_mfma_f32_16x16x32_bf16 v[40:43], v[132:135], v[214:217], v[40:43]
	v_mfma_f32_16x16x32_bf16 v[32:35], v[160:163], v[214:217], v[32:35]
	v_mfma_f32_16x16x32_bf16 v[24:27], v[132:135], v[222:225], v[24:27]
	v_mfma_f32_16x16x32_bf16 v[16:19], v[160:163], v[222:225], v[16:19]
	s_setprio 0
	s_setprio 1
	v_mfma_f32_16x16x32_bf16 v[44:47], v[164:167], v[194:197], v[44:47]
	v_mfma_f32_16x16x32_bf16 v[36:39], v[172:175], v[194:197], v[36:39]
	v_mfma_f32_16x16x32_bf16 v[28:31], v[164:167], v[202:205], v[28:31]
	v_mfma_f32_16x16x32_bf16 v[20:23], v[172:175], v[202:205], v[20:23]
	v_mfma_f32_16x16x32_bf16 v[12:15], v[164:167], v[210:213], v[12:15]
	v_mfma_f32_16x16x32_bf16 v[8:11], v[172:175], v[210:213], v[8:11]
	v_mfma_f32_16x16x32_bf16 v[4:7], v[164:167], v[218:221], v[4:7]
	v_mfma_f32_16x16x32_bf16 v[0:3], v[172:175], v[218:221], v[0:3]
	v_mfma_f32_16x16x32_bf16 v[44:47], v[168:171], v[198:201], v[44:47]
	v_mfma_f32_16x16x32_bf16 v[36:39], v[176:179], v[198:201], v[36:39]
	v_mfma_f32_16x16x32_bf16 v[28:31], v[168:171], v[206:209], v[28:31]
	v_mfma_f32_16x16x32_bf16 v[20:23], v[176:179], v[206:209], v[20:23]
	v_mfma_f32_16x16x32_bf16 v[12:15], v[168:171], v[214:217], v[12:15]
	v_mfma_f32_16x16x32_bf16 v[8:11], v[176:179], v[214:217], v[8:11]
	v_mfma_f32_16x16x32_bf16 v[4:7], v[168:171], v[222:225], v[4:7]
	v_mfma_f32_16x16x32_bf16 v[0:3], v[176:179], v[222:225], v[0:3]
	s_setprio 0
	s_barrier
	s_add_u32 s55, s55, 0x100
	s_addc_u32 s56, s56, 0
	s_cmp_ge_u32 s57, s53
	s_mov_b64 s[24:25], s[26:27]
	s_mov_b32 s28, s57
	s_cbranch_scc0 .LBB0_1246
	s_and_b64 vcc, exec, s[12:13]
	s_cbranch_vccz .LBB0_1251
	s_barrier
	s_cmp_lt_i32 s2, 0
	s_mov_b64 s[24:25], -1
	s_cbranch_scc1 .LBB0_1252
